# P3 and P4 loops: LDS-DMA loads in saddr form; re-stagger barrier moved after the tile header in P3/P4 as well
# baseline (speedup 1.0000x reference)
; template <class Epi, class Sched>
; __device__ __forceinline__ void gemm_phase(LAS unsigned char* lds, const Gemm g, const Sched& S, const Epi& E) {
;     ...
;     for (int i = 0; i < 2; ++i) { int R, C; stage_rc(tid * 16 + i * 8192, R, C); const int Rb = Epi::PERM ? ((R & ~31) + perm32(R & 31)) : R;
;         voffA[i] = (unsigned)(R * g.lda + C) * 2u; voffB[i] = (unsigned)(Rb * K + C) * 2u; }
;     const size_t kstep = (size_t)(BK * 2);
;     const size_t hstepA = (size_t)HALF * g.lda * 2, hstepB = (size_t)HALF * K * 2;
;     const size_t tstepA = 2 * hstepA, tstepB = 2 * hstepB;
;     const unsigned ldsw = (unsigned)wid * 1024u;
;     const int aoff = lds_byte(wr * 64 + fr, fq * 8), boff = lds_byte(wc * 32 + fr, fq * 8);
;     ...
;     Unit cur, nxt; int ui = 0;
;     if (!S.next(0, cur)) return;
;     f32x4 acc[2][2][4][2];
; #pragma unroll
;     for (int a = 0; a < 2; ++a)
; #pragma unroll
;         for (int b = 0; b < 2; ++b)
; #pragma unroll
;             for (int m = 0; m < 4; ++m)
; #pragma unroll
;                 for (int n = 0; n < 2; ++n) acc[a][b][m][n] = (f32x4){0.f, 0.f, 0.f, 0.f};
;     bf16x8 At[4][2], B0[2][2], B1[2][2];
; __global__ void __launch_bounds__(NTHREADS, 2) fwd_kernel(Args a) {
;     ...
;             const int l = ph / PH_PER_LAYER, k = ph - l * PH_PER_LAYER;
;             if (k == 0) phase_p0(a, lds, l);
;             else if (k == 1) {
;                 pg8::Gemm g{(const bf16_t*)(a.ws + WS_H), (const bf16_t*)(a.ws + WS_WIN), DM, DM, 0, 0};
;                 pg8::TileOrder S; S.init(MTOK, NIN, G, (int)blockIdx.x, 1, WGM_P1);
;                 pg8::EpiProj E{P};
;                 pg8::gemm_phase<pg8::EpiProj, pg8::TileOrder>(lds, g, S, E);
;             } else if (k == 2) {
;                 for (int u = blockIdx.x; u < 512; u += G) { const int nb = u & 255; const bool bc_first = (nb & 1) != 0; const bool second = (u >= 256);
;                     if (bc_first != second) mixer_bc(a, lds, P, l, nb); else mixer_a(a, lds, P, l, nb); }
;             } else if (k == 3) {
;                 pg8::Gemm g{P + S_YA, (const bf16_t*)(a.ws + WS_WABC), LDP, DM, (size_t)Y_STRIDE, (size_t)DM * DM};
;                 pg8::TileOrder S; S.init(MTOK, DM, G, (int)blockIdx.x, 3, WGM_P3);
;                 pg8::EpiGate E{P};
;                 pg8::gemm_phase<pg8::EpiGate, pg8::TileOrder>(lds, g, S, E);
.LBB0_12:
	s_cmp_lg_u32 s94, 20
	s_mov_b64 s[0:1], -1
	s_cbranch_scc0 .LBB0_767
	s_mul_hi_i32 s0, s94, 0x66666667
	s_lshr_b32 s1, s0, 31
	s_ashr_i32 s0, s0, 1
	s_add_i32 s2, s0, s1
	s_mov_b32 s0, s2
	v_writelane_b32 v255, s0, 41
	s_mov_b64 s[4:5], 0
	s_nop 0
	v_writelane_b32 v255, s1, 42
	s_mul_i32 s0, s2, -5
	s_add_i32 s2, s0, s94
	v_writelane_b32 v255, s2, 43
	v_writelane_b32 v255, s4, 44
	s_mov_b64 s[0:1], -1
	s_cmp_lt_i32 s2, 2
	v_writelane_b32 v255, s5, 45
	s_cbranch_scc1 .LBB0_269
	v_readlane_b32 s0, v255, 43
	s_cmp_gt_i32 s0, 2
	s_cbranch_scc0 .LBB0_103
	s_cmp_eq_u32 s0, 3
	s_mov_b64 s[0:1], -1
	s_movk_i32 s3, 0x2000
	s_cbranch_scc0 .LBB0_106
	v_readlane_b32 s0, v253, 2
	s_waitcnt vmcnt(0)
	v_mov_b32_e32 v1, v248
	v_readlane_b32 s1, v253, 3
	s_andn2_b64 vcc, exec, s[0:1]
	v_readfirstlane_b32 s0, v1
	s_cbranch_vccnz .LBB0_105
	s_mov_b32 s61, 0
	v_lshlrev_b32_e32 v4, 4, v1
	v_add_u32_e32 v2, 0x2000, v4
	v_ashrrev_i32_e32 v0, 31, v2
	v_lshrrev_b32_e32 v0, 22, v0
	v_add_u32_e32 v0, v2, v0
	v_ashrrev_i32_e32 v0, 10, v0
	v_mul_i32_i24_e32 v3, 0x400, v0
	v_sub_u32_e32 v2, v2, v3
	v_lshrrev_b32_e32 v3, 4, v2
	v_bitop3_b32 v3, v3, v2, 32 bitop3:0x6c
	v_ashrrev_i32_e32 v2, 31, v3
	v_lshrrev_b32_e32 v2, 26, v2
	v_add_u32_e32 v5, v3, v2
	v_lshlrev_b32_e32 v6, 3, v0
	v_ashrrev_i32_e32 v2, 6, v5
	v_and_b32_e32 v6, -16, v6
	v_add_u32_e32 v6, v2, v6
	v_and_b32_e32 v7, 3, v2
	s_mov_b32 s4, 0x1fffe0
	v_lshrrev_b32_e32 v8, 2, v6
	v_lshlrev_b32_e32 v9, 1, v6
	v_and_b32_e32 v5, 0xc0, v5
	v_and_or_b32 v7, v6, s4, v7
	v_and_b32_e32 v8, 4, v8
	v_and_b32_e32 v9, 24, v9
	v_sub_u32_e32 v3, v3, v5
	v_mov_b32_e32 v12, 1
	v_or3_b32 v7, v7, v8, v9
	v_lshlrev_b32_e32 v8, 5, v0
	v_ashrrev_i16_sdwa v3, v12, sext(v3) dst_sel:DWORD dst_unused:UNUSED_PAD src0_sel:DWORD src1_sel:BYTE_0
	v_and_b32_e32 v8, 32, v8
	v_bfe_i32 v3, v3, 0, 16
	v_add_lshl_u32 v5, v8, v3, 1
	v_lshl_add_u32 v196, v7, 11, v5
	v_lshl_add_u32 v198, v6, 11, v5
	v_bfe_i32 v5, v1, 27, 1
	v_lshrrev_b32_e32 v5, 22, v5
	v_add_u32_e32 v5, v4, v5
	v_and_b32_e32 v5, 0xfffffc00, v5
	v_sub_u32_e32 v4, v4, v5
	v_lshrrev_b32_e32 v5, 4, v4
	v_bitop3_b32 v6, v5, v4, 32 bitop3:0x6c
	v_ashrrev_i32_e32 v5, 31, v1
	v_lshrrev_b32_e32 v5, 26, v5
	v_ashrrev_i32_e32 v4, 31, v6
	v_add_u32_e32 v5, v1, v5
	v_lshrrev_b32_e32 v4, 26, v4
	v_ashrrev_i32_e32 v5, 6, v5
	v_add_u32_e32 v7, v6, v4
	v_lshlrev_b32_e32 v8, 3, v5
	v_ashrrev_i32_e32 v4, 6, v7
	v_and_b32_e32 v8, -16, v8
	v_add_u32_e32 v8, v4, v8
	v_and_b32_e32 v9, 3, v4
	v_lshrrev_b32_e32 v10, 2, v8
	v_lshlrev_b32_e32 v11, 1, v8
	v_and_b32_e32 v7, 0xc0, v7
	v_and_or_b32 v9, v8, s4, v9
	v_and_b32_e32 v10, 4, v10
	v_and_b32_e32 v11, 24, v11
	v_sub_u32_e32 v6, v6, v7
	s_ashr_i32 s1, s0, 6
	v_or3_b32 v9, v9, v10, v11
	v_lshlrev_b32_e32 v10, 5, v5
	v_ashrrev_i16_sdwa v6, v12, sext(v6) dst_sel:DWORD dst_unused:UNUSED_PAD src0_sel:DWORD src1_sel:BYTE_0
	s_lshl_b32 s2, s1, 10
	v_and_b32_e32 v10, 32, v10
	v_bfe_i32 v6, v6, 0, 16
	v_add_lshl_u32 v7, v10, v6, 1
	s_add_i32 s6, s2, 0
	v_readlane_b32 s4, v254, 56
	v_lshl_add_u32 v200, v9, 11, v7
	s_add_i32 m0, s6, 0x10000
	v_readlane_b32 s5, v254, 57
	v_lshl_add_u32 v202, v8, 11, v7
	s_add_i32 s44, s6, 0x2000
	s_add_i32 s45, s6, 0x4000
	s_add_i32 s46, s6, 0x6000
	s_ashr_i32 s14, s0, 8
	global_load_lds_dwordx4 v200, s[4:5]
	s_add_i32 m0, s6, 0x12000
	s_nop 0
	global_load_lds_dwordx4 v196, s[4:5]
	v_readlane_b32 s4, v254, 50
	s_add_i32 m0, s6, 0x14000
	v_readlane_b32 s5, v254, 51
	s_nop 4
	global_load_lds_dwordx4 v200, s[4:5]
	s_add_i32 m0, s6, 0x16000
	s_cmp_eq_u32 s14, 1
	global_load_lds_dwordx4 v196, s[4:5]
	v_readlane_b32 s4, v254, 52
	s_mov_b32 m0, s6
	v_readlane_b32 s5, v254, 53
	s_nop 4
	global_load_lds_dwordx4 v202, s[4:5]
	s_mov_b32 m0, s44
	s_nop 0
	global_load_lds_dwordx4 v198, s[4:5]
	v_readlane_b32 s4, v254, 54
	s_mov_b32 m0, s45
	v_readlane_b32 s5, v254, 55
	s_nop 4
	global_load_lds_dwordx4 v202, s[4:5]
	s_mov_b32 m0, s46
	s_nop 0
	global_load_lds_dwordx4 v198, s[4:5]
	s_cselect_b64 s[4:5], -1, 0
	s_cmp_lg_u32 s14, 1
	s_cbranch_scc1 .LBB0_19
	s_barrier

; #define PG8_STAGE(bufoff, gbase, voff) do { _Pragma("unroll") for (int _i = 0; _i < 2; ++_i) \
;         __builtin_amdgcn_global_load_lds((const unsigned*)((const char*)(gbase) + (voff)[_i]), (LAS unsigned*)(lds + (bufoff) + ldsw + _i * 8192), 16, 0, 0); } while (0)
; #define PG8_LDA(dst, b, h) do { _Pragma("unroll") for (int m = 0; m < 4; ++m) _Pragma("unroll") for (int k = 0; k < 2; ++k) dst[m][k] = *(const LAS bf16x8*)(lds + PG8_SA(b, h) + aoff + m * 2048 + k * 1024); } while (0)
; #define PG8_LDB(dst, b, h) do { _Pragma("unroll") for (int n = 0; n < 2; ++n) _Pragma("unroll") for (int k = 0; k < 2; ++k) dst[n][k] = *(const LAS bf16x8*)(lds + PG8_SB(b, h) + boff + n * 2048 + k * 1024); } while (0)
; #define PG8_MMA(ai, bj, At, Bt) do { __builtin_amdgcn_s_setprio(1); _Pragma("unroll") for (int m = 0; m < 4; ++m) _Pragma("unroll") for (int n = 0; n < 2; ++n) _Pragma("unroll") for (int k = 0; k < 2; ++k) \
;         acc[ai][bj][m][n] = __builtin_amdgcn_mfma_f32_16x16x32_bf16(Bt[n][k], At[m][k], acc[ai][bj][m][n], 0, 0, 0); __builtin_amdgcn_s_setprio(0); } while (0)
; #define PG8_BAR __builtin_amdgcn_s_barrier()
; template <class Epi, class Sched>
; __device__ __forceinline__ void gemm_phase(LAS unsigned char* lds, const Gemm g, const Sched& S, const Epi& E) {
;     ...
;         const bool has_next = S.next(ui + 1, nxt);
;         const char* nA = has_next ? (const char*)g.A + (size_t)nxt.b * g.abs * 2 + (size_t)nxt.pm * tstepA : cA;
;         const char* nB = has_next ? (const char*)g.Bt + (size_t)nxt.b * g.bbs * 2 + (size_t)nxt.pn * tstepB : cB;
;         for (int t = 0; t < nt; t += 2) {
;             const bool last = (t == nt - 2);
;             const char* a1 = cA + (size_t)(t + 1) * kstep;
;             const char* a2 = last ? nA : cA + (size_t)(t + 2) * kstep; const char* b2 = last ? nB : cB + (size_t)(t + 2) * kstep;
;             const char* a3 = a2 + kstep; const char* b3 = b2 + kstep;
;             PG8_LDB(B0, 0, 0); PG8_LDB(B1, 0, 1); PG8_SCHED; PG8_LDA(At, 0, 0); PG8_STAGE(PG8_SA(1, 1), a1 + hstepA, voffA);
;             PG8_WAIT_V(8); PG8_WAIT_L(0); PG8_BAR; PG8_MMA(0, 0, At, B0); PG8_MMA(0, 1, At, B1); PG8_BAR; PG8_SCHED;
;             PG8_LDA(At, 0, 1); PG8_STAGE(PG8_SB(0, 0), b2, voffB); PG8_STAGE(PG8_SB(0, 1), b2 + hstepB, voffB); PG8_STAGE(PG8_SA(0, 0), a2, voffA);
;     ...
;         cur = nxt; cA = nA; cB = nB; ++ui;
;         if (wr == 1) PG8_BAR;
.LBB0_30:
	s_lshl_b64 s[14:15], s[20:21], 21
	v_readlane_b32 s36, v254, 48
	v_readlane_b32 s37, v254, 49
	s_add_u32 s21, s36, s14
	s_addc_u32 s25, s37, s15
	s_ashr_i32 s23, s22, 31
	s_lshl_b64 s[14:15], s[22:23], 19
	s_add_u32 s36, s21, s14
	s_addc_u32 s37, s25, s15
	s_and_b64 s[0:1], s[0:1], exec
	s_cselect_b32 s14, s37, s17
	s_cselect_b32 s15, s36, s16
	s_add_u32 s0, s40, 0x40080
	s_addc_u32 s1, s41, 0
	s_add_u32 s21, s16, 0x100
	s_addc_u32 s23, s17, 0
	s_mov_b32 s25, -2
	s_cmp_eq_u32 s61, 0
	s_cbranch_scc1 .Lp3_nobar
	s_mov_b32 s61, 0
	s_barrier
.Lp3_nobar:
.LBB0_31:
	s_add_u32 s16, s0, 0xfffc0080
	s_addc_u32 s17, s1, -1
	s_add_i32 s52, 0, 0x10000
	s_cmp_eq_u32 s25, 12
	s_cselect_b32 s41, s27, s17
	s_cselect_b32 s40, s26, s16
	s_cselect_b32 s17, s14, s23
	s_cselect_b32 s16, s15, s21
	s_add_i32 s54, 0, 0x14000
	v_add_u32_e32 v76, s52, v221
	v_add_u32_e32 v116, s54, v221
	ds_read_b128 v[40:43], v76
	ds_read_b128 v[44:47], v76 offset:1024
	ds_read_b128 v[72:75], v76 offset:2048
	ds_read_b128 v[76:79], v76 offset:3072
	ds_read_b128 v[88:91], v116
	ds_read_b128 v[108:111], v116 offset:1024
	ds_read_b128 v[112:115], v116 offset:2048
	ds_read_b128 v[116:119], v116 offset:3072
	s_add_i32 m0, s6, 0xc000
	ds_read_b128 v[128:131], v223
	ds_read_b128 v[148:151], v223 offset:1024
	ds_read_b128 v[152:155], v223 offset:2048
	ds_read_b128 v[156:159], v223 offset:3072
	ds_read_b128 v[160:163], v223 offset:4096
	ds_read_b128 v[172:175], v223 offset:5120
	ds_read_b128 v[176:179], v223 offset:6144
	ds_read_b128 v[188:191], v223 offset:7168
	global_load_lds_dwordx4 v204, s[0:1]
	s_add_i32 m0, s6, 0xe000
	s_nop 0
	global_load_lds_dwordx4 v206, s[0:1]
	s_waitcnt vmcnt(8)
	s_waitcnt lgkmcnt(0)
	s_barrier
	s_setprio 1
	s_waitcnt lgkmcnt(0)
	v_mfma_f32_16x16x32_bf16 v[60:63], v[40:43], v[128:131], v[60:63]
	v_mfma_f32_16x16x32_bf16 v[56:59], v[72:75], v[128:131], v[56:59]
	v_mfma_f32_16x16x32_bf16 v[96:99], v[40:43], v[152:155], v[96:99]
	v_mfma_f32_16x16x32_bf16 v[92:95], v[72:75], v[152:155], v[92:95]
	v_mfma_f32_16x16x32_bf16 v[136:139], v[40:43], v[160:163], v[136:139]
	v_mfma_f32_16x16x32_bf16 v[132:135], v[72:75], v[160:163], v[132:135]
	v_mfma_f32_16x16x32_bf16 v[124:127], v[40:43], v[176:179], v[124:127]
	v_mfma_f32_16x16x32_bf16 v[120:123], v[72:75], v[176:179], v[120:123]
	v_mfma_f32_16x16x32_bf16 v[60:63], v[44:47], v[148:151], v[60:63]
	v_mfma_f32_16x16x32_bf16 v[56:59], v[76:79], v[148:151], v[56:59]
	v_mfma_f32_16x16x32_bf16 v[96:99], v[44:47], v[156:159], v[96:99]
	v_mfma_f32_16x16x32_bf16 v[92:95], v[76:79], v[156:159], v[92:95]
	v_mfma_f32_16x16x32_bf16 v[136:139], v[44:47], v[172:175], v[136:139]
	v_mfma_f32_16x16x32_bf16 v[132:135], v[76:79], v[172:175], v[132:135]
	v_mfma_f32_16x16x32_bf16 v[124:127], v[44:47], v[188:191], v[124:127]
	v_mfma_f32_16x16x32_bf16 v[120:123], v[76:79], v[188:191], v[120:123]
	s_setprio 0
	s_setprio 1
	v_mfma_f32_16x16x32_bf16 v[184:187], v[88:91], v[128:131], v[184:187]
	v_mfma_f32_16x16x32_bf16 v[128:131], v[112:115], v[128:131], v[180:183]
	v_mfma_f32_16x16x32_bf16 v[144:147], v[88:91], v[160:163], v[144:147]
	v_mfma_f32_16x16x32_bf16 v[140:143], v[112:115], v[160:163], v[140:143]
	v_mfma_f32_16x16x32_bf16 v[104:107], v[88:91], v[176:179], v[104:107]
	v_mfma_f32_16x16x32_bf16 v[100:103], v[112:115], v[176:179], v[100:103]
	v_mfma_f32_16x16x32_bf16 v[184:187], v[108:111], v[148:151], v[184:187]
	v_mfma_f32_16x16x32_bf16 v[128:131], v[116:119], v[148:151], v[128:131]
	v_mfma_f32_16x16x32_bf16 v[148:151], v[88:91], v[152:155], v[168:171]
	v_mfma_f32_16x16x32_bf16 v[152:155], v[112:115], v[152:155], v[164:167]
	v_mfma_f32_16x16x32_bf16 v[144:147], v[108:111], v[172:175], v[144:147]
	v_mfma_f32_16x16x32_bf16 v[140:143], v[116:119], v[172:175], v[140:143]
	v_mfma_f32_16x16x32_bf16 v[104:107], v[108:111], v[188:191], v[104:107]
	v_mfma_f32_16x16x32_bf16 v[100:103], v[116:119], v[188:191], v[100:103]
	v_mfma_f32_16x16x32_bf16 v[148:151], v[108:111], v[156:159], v[148:151]
	v_mfma_f32_16x16x32_bf16 v[152:155], v[116:119], v[156:159], v[152:155]
	s_setprio 0
	s_barrier
	s_add_i32 s52, s52, s2
	s_mov_b32 m0, s52
	ds_read_b128 v[156:159], v223 offset:16384
	ds_read_b128 v[160:163], v223 offset:17408
	ds_read_b128 v[164:167], v223 offset:18432
	ds_read_b128 v[168:171], v223 offset:19456
	ds_read_b128 v[172:175], v223 offset:20480
	ds_read_b128 v[176:179], v223 offset:21504
	ds_read_b128 v[180:183], v223 offset:22528
	ds_read_b128 v[188:191], v223 offset:23552
	global_load_lds_dwordx4 v200, s[16:17]
	s_add_i32 m0, s52, 0x2000
	s_add_u32 s52, s16, 0x40000
	s_addc_u32 s53, s17, 0
	s_add_i32 s54, s54, s2
	global_load_lds_dwordx4 v196, s[16:17]
	s_mov_b32 m0, s54
	s_nop 0
	global_load_lds_dwordx4 v200, s[52:53]
	s_add_i32 m0, s54, 0x2000
	s_nop 0
	global_load_lds_dwordx4 v196, s[52:53]
	s_mov_b32 m0, s6
	s_nop 0
	global_load_lds_dwordx4 v202, s[40:41]
	s_mov_b32 m0, s44
	s_nop 0
	global_load_lds_dwordx4 v198, s[40:41]
	s_waitcnt vmcnt(8)
	s_waitcnt lgkmcnt(0)
	s_barrier
; #define PG8_STAGE(bufoff, gbase, voff) do { _Pragma("unroll") for (int _i = 0; _i < 2; ++_i) \
;         __builtin_amdgcn_global_load_lds((const unsigned*)((const char*)(gbase) + (voff)[_i]), (LAS unsigned*)(lds + (bufoff) + ldsw + _i * 8192), 16, 0, 0); } while (0)
; #define PG8_LDA(dst, b, h) do { _Pragma("unroll") for (int m = 0; m < 4; ++m) _Pragma("unroll") for (int k = 0; k < 2; ++k) dst[m][k] = *(const LAS bf16x8*)(lds + PG8_SA(b, h) + aoff + m * 2048 + k * 1024); } while (0)
; #define PG8_LDB(dst, b, h) do { _Pragma("unroll") for (int n = 0; n < 2; ++n) _Pragma("unroll") for (int k = 0; k < 2; ++k) dst[n][k] = *(const LAS bf16x8*)(lds + PG8_SB(b, h) + boff + n * 2048 + k * 1024); } while (0)
; #define PG8_MMA(ai, bj, At, Bt) do { __builtin_amdgcn_s_setprio(1); _Pragma("unroll") for (int m = 0; m < 4; ++m) _Pragma("unroll") for (int n = 0; n < 2; ++n) _Pragma("unroll") for (int k = 0; k < 2; ++k) \
;         acc[ai][bj][m][n] = __builtin_amdgcn_mfma_f32_16x16x32_bf16(Bt[n][k], At[m][k], acc[ai][bj][m][n], 0, 0, 0); __builtin_amdgcn_s_setprio(0); } while (0)
; #define PG8_WAIT_V(n) asm volatile("s_waitcnt vmcnt(" #n ")" ::: "memory")
; #define PG8_WAIT_L(n) asm volatile("s_waitcnt lgkmcnt(" #n ")" ::: "memory")
; #define PG8_BAR __builtin_amdgcn_s_barrier()
; #define PG8_SCHED __builtin_amdgcn_sched_barrier(0)
; template <class Epi, class Sched>
; __device__ __forceinline__ void gemm_phase(LAS unsigned char* lds, const Gemm g, const Sched& S, const Epi& E) {
;     ...
;             PG8_WAIT_V(8); PG8_WAIT_L(0); PG8_BAR; PG8_MMA(1, 0, At, B0); PG8_MMA(1, 1, At, B1); PG8_BAR; PG8_SCHED;
;             PG8_LDB(B0, 1, 0); PG8_LDB(B1, 1, 1); PG8_SCHED; PG8_LDA(At, 1, 0); PG8_STAGE(PG8_SA(0, 1), a2 + hstepA, voffA);
;             PG8_WAIT_V(8); PG8_WAIT_L(0); PG8_BAR; PG8_MMA(0, 0, At, B0); PG8_MMA(0, 1, At, B1); PG8_BAR; PG8_SCHED;
	s_setprio 1
	s_waitcnt lgkmcnt(0)
	v_mfma_f32_16x16x32_bf16 v[84:87], v[40:43], v[156:159], v[84:87]
	v_mfma_f32_16x16x32_bf16 v[80:83], v[72:75], v[156:159], v[80:83]
	v_mfma_f32_16x16x32_bf16 v[52:55], v[40:43], v[164:167], v[52:55]
	v_mfma_f32_16x16x32_bf16 v[48:51], v[72:75], v[164:167], v[48:51]
	v_mfma_f32_16x16x32_bf16 v[28:31], v[40:43], v[172:175], v[28:31]
	v_mfma_f32_16x16x32_bf16 v[24:27], v[72:75], v[172:175], v[24:27]
	v_mfma_f32_16x16x32_bf16 v[12:15], v[40:43], v[180:183], v[12:15]
	v_mfma_f32_16x16x32_bf16 v[8:11], v[72:75], v[180:183], v[8:11]
	v_mfma_f32_16x16x32_bf16 v[84:87], v[44:47], v[160:163], v[84:87]
	v_mfma_f32_16x16x32_bf16 v[80:83], v[76:79], v[160:163], v[80:83]
	v_mfma_f32_16x16x32_bf16 v[52:55], v[44:47], v[168:171], v[52:55]
	v_mfma_f32_16x16x32_bf16 v[48:51], v[76:79], v[168:171], v[48:51]
	v_mfma_f32_16x16x32_bf16 v[28:31], v[44:47], v[176:179], v[28:31]
	v_mfma_f32_16x16x32_bf16 v[24:27], v[76:79], v[176:179], v[24:27]
	v_mfma_f32_16x16x32_bf16 v[12:15], v[44:47], v[188:191], v[12:15]
	v_mfma_f32_16x16x32_bf16 v[8:11], v[76:79], v[188:191], v[8:11]
	s_setprio 0
	s_setprio 1
	v_mfma_f32_16x16x32_bf16 v[36:39], v[88:91], v[164:167], v[36:39]
	v_mfma_f32_16x16x32_bf16 v[32:35], v[112:115], v[164:167], v[32:35]
	v_mfma_f32_16x16x32_bf16 v[20:23], v[88:91], v[172:175], v[20:23]
	v_mfma_f32_16x16x32_bf16 v[16:19], v[112:115], v[172:175], v[16:19]
	v_mfma_f32_16x16x32_bf16 v[4:7], v[88:91], v[180:183], v[4:7]
	v_mfma_f32_16x16x32_bf16 v[0:3], v[112:115], v[180:183], v[0:3]
	v_mfma_f32_16x16x32_bf16 v[40:43], v[88:91], v[156:159], v[68:71]
	v_mfma_f32_16x16x32_bf16 v[44:47], v[112:115], v[156:159], v[64:67]
	v_mfma_f32_16x16x32_bf16 v[36:39], v[108:111], v[168:171], v[36:39]
	v_mfma_f32_16x16x32_bf16 v[32:35], v[116:119], v[168:171], v[32:35]
	v_mfma_f32_16x16x32_bf16 v[20:23], v[108:111], v[176:179], v[20:23]
	v_mfma_f32_16x16x32_bf16 v[16:19], v[116:119], v[176:179], v[16:19]
	v_mfma_f32_16x16x32_bf16 v[4:7], v[108:111], v[188:191], v[4:7]
	v_mfma_f32_16x16x32_bf16 v[0:3], v[116:119], v[188:191], v[0:3]
	v_mfma_f32_16x16x32_bf16 v[40:43], v[108:111], v[160:163], v[40:43]
	v_mfma_f32_16x16x32_bf16 v[44:47], v[116:119], v[160:163], v[44:47]
	s_setprio 0
	s_barrier
	s_add_i32 s52, 0, 0x18000
	s_add_i32 s53, 0, 0x1c000
	v_add_u32_e32 v76, s52, v221
	v_add_u32_e32 v116, s53, v221
	ds_read_b128 v[64:67], v76
	ds_read_b128 v[68:71], v76 offset:1024
	ds_read_b128 v[72:75], v76 offset:2048
	ds_read_b128 v[76:79], v76 offset:3072
	ds_read_b128 v[88:91], v116
	ds_read_b128 v[108:111], v116 offset:1024
	ds_read_b128 v[112:115], v116 offset:2048
	ds_read_b128 v[116:119], v116 offset:3072
	s_add_u32 s40, s40, 0x40000
	s_addc_u32 s41, s41, 0
	s_mov_b32 m0, s45
	ds_read_b128 v[156:159], v223 offset:32768
	ds_read_b128 v[160:163], v223 offset:33792
	ds_read_b128 v[164:167], v223 offset:34816
	ds_read_b128 v[172:175], v223 offset:35840
	ds_read_b128 v[176:179], v223 offset:36864
	ds_read_b128 v[188:191], v223 offset:37888
	ds_read_b128 v[192:195], v223 offset:38912
	ds_read_b128 v[208:211], v223 offset:39936
	global_load_lds_dwordx4 v202, s[40:41]
	s_mov_b32 m0, s46
	s_nop 0
	global_load_lds_dwordx4 v198, s[40:41]
	s_waitcnt vmcnt(8)
	s_waitcnt lgkmcnt(0)
	s_barrier
	s_setprio 1
	s_waitcnt lgkmcnt(0)
	v_mfma_f32_16x16x32_bf16 v[60:63], v[64:67], v[156:159], v[60:63]
	v_mfma_f32_16x16x32_bf16 v[56:59], v[72:75], v[156:159], v[56:59]
	v_mfma_f32_16x16x32_bf16 v[96:99], v[64:67], v[164:167], v[96:99]
	v_mfma_f32_16x16x32_bf16 v[92:95], v[72:75], v[164:167], v[92:95]
	v_mfma_f32_16x16x32_bf16 v[136:139], v[64:67], v[176:179], v[136:139]
	v_mfma_f32_16x16x32_bf16 v[132:135], v[72:75], v[176:179], v[132:135]
	v_mfma_f32_16x16x32_bf16 v[124:127], v[64:67], v[192:195], v[124:127]
	v_mfma_f32_16x16x32_bf16 v[120:123], v[72:75], v[192:195], v[120:123]
	v_mfma_f32_16x16x32_bf16 v[60:63], v[68:71], v[160:163], v[60:63]
	v_mfma_f32_16x16x32_bf16 v[56:59], v[76:79], v[160:163], v[56:59]
	v_mfma_f32_16x16x32_bf16 v[96:99], v[68:71], v[172:175], v[96:99]
	v_mfma_f32_16x16x32_bf16 v[92:95], v[76:79], v[172:175], v[92:95]
	v_mfma_f32_16x16x32_bf16 v[136:139], v[68:71], v[188:191], v[136:139]
	v_mfma_f32_16x16x32_bf16 v[132:135], v[76:79], v[188:191], v[132:135]
	v_mfma_f32_16x16x32_bf16 v[124:127], v[68:71], v[208:211], v[124:127]
	v_mfma_f32_16x16x32_bf16 v[120:123], v[76:79], v[208:211], v[120:123]
	s_setprio 0
	s_setprio 1
	v_mfma_f32_16x16x32_bf16 v[128:131], v[112:115], v[156:159], v[128:131]
	v_mfma_f32_16x16x32_bf16 v[168:171], v[88:91], v[156:159], v[184:187]
	v_mfma_f32_16x16x32_bf16 v[180:183], v[116:119], v[160:163], v[128:131]
	v_mfma_f32_16x16x32_bf16 v[128:131], v[88:91], v[164:167], v[148:151]
	v_mfma_f32_16x16x32_bf16 v[184:187], v[108:111], v[160:163], v[168:171]
	v_mfma_f32_16x16x32_bf16 v[168:171], v[108:111], v[172:175], v[128:131]
	v_mfma_f32_16x16x32_bf16 v[128:131], v[112:115], v[164:167], v[152:155]
	v_mfma_f32_16x16x32_bf16 v[164:167], v[116:119], v[172:175], v[128:131]
	v_mfma_f32_16x16x32_bf16 v[128:131], v[88:91], v[176:179], v[144:147]
	v_mfma_f32_16x16x32_bf16 v[144:147], v[108:111], v[188:191], v[128:131]
	v_mfma_f32_16x16x32_bf16 v[128:131], v[112:115], v[176:179], v[140:143]
	v_mfma_f32_16x16x32_bf16 v[104:107], v[88:91], v[192:195], v[104:107]
	v_mfma_f32_16x16x32_bf16 v[100:103], v[112:115], v[192:195], v[100:103]
	v_mfma_f32_16x16x32_bf16 v[140:143], v[116:119], v[188:191], v[128:131]
	v_mfma_f32_16x16x32_bf16 v[104:107], v[108:111], v[208:211], v[104:107]
	v_mfma_f32_16x16x32_bf16 v[100:103], v[116:119], v[208:211], v[100:103]
	s_setprio 0
	s_barrier
; #define PG8_STAGE(bufoff, gbase, voff) do { _Pragma("unroll") for (int _i = 0; _i < 2; ++_i) \
;         __builtin_amdgcn_global_load_lds((const unsigned*)((const char*)(gbase) + (voff)[_i]), (LAS unsigned*)(lds + (bufoff) + ldsw + _i * 8192), 16, 0, 0); } while (0)
; #define PG8_LDA(dst, b, h) do { _Pragma("unroll") for (int m = 0; m < 4; ++m) _Pragma("unroll") for (int k = 0; k < 2; ++k) dst[m][k] = *(const LAS bf16x8*)(lds + PG8_SA(b, h) + aoff + m * 2048 + k * 1024); } while (0)
; #define PG8_MMA(ai, bj, At, Bt) do { __builtin_amdgcn_s_setprio(1); _Pragma("unroll") for (int m = 0; m < 4; ++m) _Pragma("unroll") for (int n = 0; n < 2; ++n) _Pragma("unroll") for (int k = 0; k < 2; ++k) \
;         acc[ai][bj][m][n] = __builtin_amdgcn_mfma_f32_16x16x32_bf16(Bt[n][k], At[m][k], acc[ai][bj][m][n], 0, 0, 0); __builtin_amdgcn_s_setprio(0); } while (0)
; #define PG8_WAIT_V(n) asm volatile("s_waitcnt vmcnt(" #n ")" ::: "memory")
; #define PG8_WAIT_L(n) asm volatile("s_waitcnt lgkmcnt(" #n ")" ::: "memory")
; #define PG8_BAR __builtin_amdgcn_s_barrier()
; #define PG8_SCHED __builtin_amdgcn_sched_barrier(0)
; template <class Epi, class Sched>
; __device__ __forceinline__ void gemm_phase(LAS unsigned char* lds, const Gemm g, const Sched& S, const Epi& E) {
;     ...
;             PG8_LDA(At, 1, 1); PG8_STAGE(PG8_SB(1, 0), b3, voffB); PG8_STAGE(PG8_SB(1, 1), b3 + hstepB, voffB); PG8_STAGE(PG8_SA(1, 0), a3, voffA);
;             PG8_WAIT_V(8); PG8_WAIT_L(0); PG8_BAR; PG8_MMA(1, 0, At, B0); PG8_MMA(1, 1, At, B1); PG8_BAR; PG8_SCHED;
;         }
;         if (wr == 0) PG8_BAR;
	s_add_u32 s98, s40, 0xfffc0080
	s_addc_u32 s99, s41, -1
	s_add_u32 s62, s16, 0x80
	s_addc_u32 s63, s17, 0
	s_add_i32 s40, s52, s2
	s_mov_b32 m0, s40
	ds_read_b128 v[128:131], v223 offset:49152
	ds_read_b128 v[148:151], v223 offset:50176
	ds_read_b128 v[152:155], v223 offset:51200
	ds_read_b128 v[156:159], v223 offset:52224
	ds_read_b128 v[160:163], v223 offset:53248
	ds_read_b128 v[172:175], v223 offset:54272
	ds_read_b128 v[176:179], v223 offset:55296
	ds_read_b128 v[188:191], v223 offset:56320
	global_load_lds_dwordx4 v200, s[62:63]
	s_add_i32 m0, s40, 0x2000
	s_add_u32 s16, s16, 0x40080
	s_addc_u32 s17, s17, 0
	s_add_i32 s40, s53, s2
	global_load_lds_dwordx4 v196, s[62:63]
	s_mov_b32 m0, s40
	s_nop 0
	global_load_lds_dwordx4 v200, s[16:17]
	s_add_i32 m0, s40, 0x2000
	s_nop 0
	global_load_lds_dwordx4 v196, s[16:17]
	s_mov_b32 m0, s47
	s_nop 0
	global_load_lds_dwordx4 v202, s[98:99]
	s_mov_b32 m0, s48
	s_nop 0
	global_load_lds_dwordx4 v198, s[98:99]
	s_waitcnt vmcnt(8)
	s_waitcnt lgkmcnt(0)
	s_barrier
	s_setprio 1
	s_waitcnt lgkmcnt(0)
	v_mfma_f32_16x16x32_bf16 v[84:87], v[64:67], v[128:131], v[84:87]
	v_mfma_f32_16x16x32_bf16 v[80:83], v[72:75], v[128:131], v[80:83]
	v_mfma_f32_16x16x32_bf16 v[52:55], v[64:67], v[152:155], v[52:55]
	v_mfma_f32_16x16x32_bf16 v[48:51], v[72:75], v[152:155], v[48:51]
	v_mfma_f32_16x16x32_bf16 v[28:31], v[64:67], v[160:163], v[28:31]
	v_mfma_f32_16x16x32_bf16 v[24:27], v[72:75], v[160:163], v[24:27]
	v_mfma_f32_16x16x32_bf16 v[12:15], v[64:67], v[176:179], v[12:15]
	v_mfma_f32_16x16x32_bf16 v[8:11], v[72:75], v[176:179], v[8:11]
	v_mfma_f32_16x16x32_bf16 v[84:87], v[68:71], v[148:151], v[84:87]
	v_mfma_f32_16x16x32_bf16 v[80:83], v[76:79], v[148:151], v[80:83]
	v_mfma_f32_16x16x32_bf16 v[52:55], v[68:71], v[156:159], v[52:55]
	v_mfma_f32_16x16x32_bf16 v[48:51], v[76:79], v[156:159], v[48:51]
	v_mfma_f32_16x16x32_bf16 v[28:31], v[68:71], v[172:175], v[28:31]
	v_mfma_f32_16x16x32_bf16 v[24:27], v[76:79], v[172:175], v[24:27]
	v_mfma_f32_16x16x32_bf16 v[12:15], v[68:71], v[188:191], v[12:15]
	v_mfma_f32_16x16x32_bf16 v[8:11], v[76:79], v[188:191], v[8:11]
	s_setprio 0
	s_setprio 1
	v_mfma_f32_16x16x32_bf16 v[40:43], v[88:91], v[128:131], v[40:43]
	v_mfma_f32_16x16x32_bf16 v[68:71], v[108:111], v[148:151], v[40:43]
	v_mfma_f32_16x16x32_bf16 v[40:43], v[112:115], v[128:131], v[44:47]
	v_mfma_f32_16x16x32_bf16 v[36:39], v[88:91], v[152:155], v[36:39]
	v_mfma_f32_16x16x32_bf16 v[32:35], v[112:115], v[152:155], v[32:35]
	v_mfma_f32_16x16x32_bf16 v[20:23], v[88:91], v[160:163], v[20:23]
	v_mfma_f32_16x16x32_bf16 v[16:19], v[112:115], v[160:163], v[16:19]
	v_mfma_f32_16x16x32_bf16 v[4:7], v[88:91], v[176:179], v[4:7]
	v_mfma_f32_16x16x32_bf16 v[0:3], v[112:115], v[176:179], v[0:3]
	v_mfma_f32_16x16x32_bf16 v[64:67], v[116:119], v[148:151], v[40:43]
	v_mfma_f32_16x16x32_bf16 v[36:39], v[108:111], v[156:159], v[36:39]
	v_mfma_f32_16x16x32_bf16 v[32:35], v[116:119], v[156:159], v[32:35]
	v_mfma_f32_16x16x32_bf16 v[20:23], v[108:111], v[172:175], v[20:23]
	v_mfma_f32_16x16x32_bf16 v[16:19], v[116:119], v[172:175], v[16:19]
	v_mfma_f32_16x16x32_bf16 v[4:7], v[108:111], v[188:191], v[4:7]
	v_mfma_f32_16x16x32_bf16 v[0:3], v[116:119], v[188:191], v[0:3]
	s_setprio 0
	s_barrier
	s_add_i32 s25, s25, 2
	s_add_u32 s0, s0, 0x100
	s_addc_u32 s1, s1, 0
	s_add_u32 s21, s21, 0x100
	s_addc_u32 s23, s23, 0
	s_cmp_gt_u32 s25, 13
	s_cbranch_scc0 .LBB0_31
	s_and_b64 vcc, exec, s[18:19]
	s_cbranch_vccz .LBB0_34
	s_barrier

; #define PG8_BAR __builtin_amdgcn_s_barrier()
; template <class Epi, class Sched>
; __device__ __forceinline__ void gemm_phase(LAS unsigned char* lds, const Gemm g, const Sched& S, const Epi& E) {
;     ...
;         cur = nxt; cA = nA; cB = nB; ++ui;
;         if (wr == 1) PG8_BAR;
.LBB0_102:
	s_mov_b32 s61, 1
	s_branch .LBB0_20

; #define PG8_WAIT_V(n) asm volatile("s_waitcnt vmcnt(" #n ")" ::: "memory")
; #define PG8_BAR __builtin_amdgcn_s_barrier()
; template <class Epi, class Sched>
; __device__ __forceinline__ void gemm_phase(LAS unsigned char* lds, const Gemm g, const Sched& S, const Epi& E) {
;     ...
;     for (int i = 0; i < 2; ++i) { int R, C; stage_rc(tid * 16 + i * 8192, R, C); const int Rb = Epi::PERM ? ((R & ~31) + perm32(R & 31)) : R;
;         voffA[i] = (unsigned)(R * g.lda + C) * 2u; voffB[i] = (unsigned)(Rb * K + C) * 2u; }
;     const size_t kstep = (size_t)(BK * 2);
;     const size_t hstepA = (size_t)HALF * g.lda * 2, hstepB = (size_t)HALF * K * 2;
;     const size_t tstepA = 2 * hstepA, tstepB = 2 * hstepB;
;     const unsigned ldsw = (unsigned)wid * 1024u;
;     const int aoff = lds_byte(wr * 64 + fr, fq * 8), boff = lds_byte(wc * 32 + fr, fq * 8);
;     ...
;     Unit cur, nxt; int ui = 0;
;     if (!S.next(0, cur)) return;
;     f32x4 acc[2][2][4][2];
; #pragma unroll
;     for (int a = 0; a < 2; ++a)
; #pragma unroll
;         for (int b = 0; b < 2; ++b)
; #pragma unroll
;             for (int m = 0; m < 4; ++m)
; #pragma unroll
;                 for (int n = 0; n < 2; ++n) acc[a][b][m][n] = (f32x4){0.f, 0.f, 0.f, 0.f};
;     bf16x8 At[4][2], B0[2][2], B1[2][2];
;     const char* cA = (const char*)g.A + (size_t)cur.b * g.abs * 2 + (size_t)cur.pm * tstepA;
;     const char* cB = (const char*)g.Bt + (size_t)cur.b * g.bbs * 2 + (size_t)cur.pn * tstepB;
;     PG8_STAGE(PG8_SB(0, 0), cB, voffB); PG8_STAGE(PG8_SB(0, 1), cB + hstepB, voffB); PG8_STAGE(PG8_SA(0, 0), cA, voffA); PG8_STAGE(PG8_SA(0, 1), cA + hstepA, voffA);
;     if (wr == 1) PG8_BAR;
;     PG8_WAIT_V(2); PG8_BAR;
;     PG8_STAGE(PG8_SB(1, 0), cB + kstep, voffB); PG8_STAGE(PG8_SA(1, 0), cA + kstep, voffA); PG8_STAGE(PG8_SB(1, 1), cB + hstepB + kstep, voffB);
;     PG8_WAIT_V(6); PG8_BAR;
; __global__ void __launch_bounds__(NTHREADS, 2) fwd_kernel(Args a) {
;     ...
;             } else {
;                 pg8::Gemm g{P + S_MG, (const bf16_t*)(a.ws + WS_WOUT), LDP, DM, 0, 0};
;                 pg8::TileOrder S; S.init(MTOK, DM, G, (int)blockIdx.x, 1, WGM_P4);
;                 pg8::EpiRes E{(bf16_t*)(a.ws + WS_XR)};
;                 pg8::gemm_phase<pg8::EpiRes, pg8::TileOrder>(lds, g, S, E);
.LBB0_496:
	s_nop 0
	v_readlane_b32 s0, v255, 44
	v_readlane_b32 s1, v255, 45
	s_and_b64 vcc, exec, s[0:1]
	s_cbranch_vccz .LBB0_518
	v_readlane_b32 s0, v253, 2
	v_mov_b32_e32 v6, v248
	v_readlane_b32 s1, v253, 3
	s_andn2_b64 vcc, exec, s[0:1]
	v_readfirstlane_b32 s4, v6
	s_cbranch_vccnz .LBB0_517
	s_mov_b32 s61, 0
	s_waitcnt vmcnt(0)
	v_lshlrev_b32_e32 v3, 4, v6
	v_add_u32_e32 v1, 0x2000, v3
	v_ashrrev_i32_e32 v0, 31, v1
	v_lshrrev_b32_e32 v0, 22, v0
	v_add_u32_e32 v0, v1, v0
	v_ashrrev_i32_e32 v0, 10, v0
	v_mul_i32_i24_e32 v2, 0x400, v0
	v_sub_u32_e32 v1, v1, v2
	v_lshrrev_b32_e32 v2, 4, v1
	v_bitop3_b32 v2, v2, v1, 32 bitop3:0x6c
	v_ashrrev_i32_e32 v1, 31, v2
	v_lshrrev_b32_e32 v1, 26, v1
	v_add_u32_e32 v4, v2, v1
	v_lshlrev_b32_e32 v5, 3, v0
	v_ashrrev_i32_e32 v1, 6, v4
	v_and_b32_e32 v5, -16, v5
	v_add_u32_e32 v5, v1, v5
	v_and_b32_e32 v7, 3, v1
	s_mov_b32 s0, 0x1fffe0
	v_lshrrev_b32_e32 v8, 2, v5
	v_lshlrev_b32_e32 v9, 1, v5
	v_and_b32_e32 v4, 0xc0, v4
	v_and_or_b32 v7, v5, s0, v7
	v_and_b32_e32 v8, 4, v8
	v_and_b32_e32 v9, 24, v9
	v_sub_u32_e32 v2, v2, v4
	v_mov_b32_e32 v12, 1
	v_or3_b32 v7, v7, v8, v9
	v_lshlrev_b32_e32 v8, 5, v0
	v_ashrrev_i16_sdwa v2, v12, sext(v2) dst_sel:DWORD dst_unused:UNUSED_PAD src0_sel:DWORD src1_sel:BYTE_0
	v_and_b32_e32 v8, 32, v8
	v_bfe_i32 v2, v2, 0, 16
	v_add_lshl_u32 v4, v8, v2, 1
	v_lshl_add_u32 v156, v7, 11, v4
	v_lshl_add_u32 v158, v5, 11, v4
	v_bfe_i32 v4, v6, 27, 1
	v_lshrrev_b32_e32 v4, 22, v4
	v_add_u32_e32 v4, v3, v4
	v_and_b32_e32 v4, 0xfffffc00, v4
	v_sub_u32_e32 v3, v3, v4
	v_lshrrev_b32_e32 v4, 4, v3
	v_bitop3_b32 v5, v4, v3, 32 bitop3:0x6c
	v_ashrrev_i32_e32 v4, 31, v6
	v_lshrrev_b32_e32 v4, 26, v4
	v_ashrrev_i32_e32 v3, 31, v5
	v_add_u32_e32 v4, v6, v4
	v_lshrrev_b32_e32 v3, 26, v3
	v_ashrrev_i32_e32 v4, 6, v4
	v_add_u32_e32 v7, v5, v3
	v_lshlrev_b32_e32 v8, 3, v4
	v_ashrrev_i32_e32 v3, 6, v7
	v_and_b32_e32 v8, -16, v8
	v_add_u32_e32 v8, v3, v8
	v_and_b32_e32 v9, 3, v3
	v_lshrrev_b32_e32 v10, 2, v8
	v_lshlrev_b32_e32 v11, 1, v8
	v_and_b32_e32 v7, 0xc0, v7
	v_and_or_b32 v9, v8, s0, v9
	v_and_b32_e32 v10, 4, v10
	v_and_b32_e32 v11, 24, v11
	v_sub_u32_e32 v5, v5, v7
	s_ashr_i32 s5, s4, 6
	v_or3_b32 v9, v9, v10, v11
	v_lshlrev_b32_e32 v10, 5, v4
	v_ashrrev_i16_sdwa v5, v12, sext(v5) dst_sel:DWORD dst_unused:UNUSED_PAD src0_sel:DWORD src1_sel:BYTE_0
	s_lshl_b32 s2, s5, 10
	v_and_b32_e32 v10, 32, v10
	v_bfe_i32 v5, v5, 0, 16
	v_add_lshl_u32 v7, v10, v5, 1
	s_add_i32 s6, s2, 0
	v_readlane_b32 s0, v254, 44
	v_lshl_add_u32 v160, v9, 11, v7
	s_add_i32 m0, s6, 0x10000
	v_readlane_b32 s1, v254, 45
	v_lshl_add_u32 v162, v8, 11, v7
	s_add_i32 s40, s6, 0x2000
	s_add_i32 s41, s6, 0x4000
	s_add_i32 s42, s6, 0x6000
	s_ashr_i32 s14, s4, 8
	global_load_lds_dwordx4 v160, s[0:1]
	s_add_i32 m0, s6, 0x12000
	s_nop 0
	global_load_lds_dwordx4 v156, s[0:1]
	v_readlane_b32 s0, v254, 38
	s_add_i32 m0, s6, 0x14000
	v_readlane_b32 s1, v254, 39
	s_nop 4
	global_load_lds_dwordx4 v160, s[0:1]
	s_add_i32 m0, s6, 0x16000
	s_cmp_eq_u32 s14, 1
	global_load_lds_dwordx4 v156, s[0:1]
	v_readlane_b32 s0, v254, 40
	s_mov_b32 m0, s6
	v_readlane_b32 s1, v254, 41
	s_nop 4
	global_load_lds_dwordx4 v162, s[0:1]
	s_mov_b32 m0, s40
	s_nop 0
	global_load_lds_dwordx4 v158, s[0:1]
	v_readlane_b32 s0, v254, 42
	s_mov_b32 m0, s41
	v_readlane_b32 s1, v254, 43
	s_nop 4
	global_load_lds_dwordx4 v162, s[0:1]
	s_mov_b32 m0, s42
	s_nop 0
	global_load_lds_dwordx4 v158, s[0:1]
	s_cselect_b64 s[0:1], -1, 0
	s_cmp_lg_u32 s14, 1
	s_cbranch_scc1 .LBB0_500
	s_barrier

; #define PG8_STAGE(bufoff, gbase, voff) do { _Pragma("unroll") for (int _i = 0; _i < 2; ++_i) \
;         __builtin_amdgcn_global_load_lds((const unsigned*)((const char*)(gbase) + (voff)[_i]), (LAS unsigned*)(lds + (bufoff) + ldsw + _i * 8192), 16, 0, 0); } while (0)
; #define PG8_LDA(dst, b, h) do { _Pragma("unroll") for (int m = 0; m < 4; ++m) _Pragma("unroll") for (int k = 0; k < 2; ++k) dst[m][k] = *(const LAS bf16x8*)(lds + PG8_SA(b, h) + aoff + m * 2048 + k * 1024); } while (0)
; #define PG8_LDB(dst, b, h) do { _Pragma("unroll") for (int n = 0; n < 2; ++n) _Pragma("unroll") for (int k = 0; k < 2; ++k) dst[n][k] = *(const LAS bf16x8*)(lds + PG8_SB(b, h) + boff + n * 2048 + k * 1024); } while (0)
; #define PG8_BAR __builtin_amdgcn_s_barrier()
; #define PG8_SCHED __builtin_amdgcn_sched_barrier(0)
; template <class Epi, class Sched>
; __device__ __forceinline__ void gemm_phase(LAS unsigned char* lds, const Gemm g, const Sched& S, const Epi& E) {
;     ...
;         const bool has_next = S.next(ui + 1, nxt);
;         const char* nA = has_next ? (const char*)g.A + (size_t)nxt.b * g.abs * 2 + (size_t)nxt.pm * tstepA : cA;
;         const char* nB = has_next ? (const char*)g.Bt + (size_t)nxt.b * g.bbs * 2 + (size_t)nxt.pn * tstepB : cB;
;         for (int t = 0; t < nt; t += 2) {
;             const bool last = (t == nt - 2);
;             const char* a1 = cA + (size_t)(t + 1) * kstep;
;             const char* a2 = last ? nA : cA + (size_t)(t + 2) * kstep; const char* b2 = last ? nB : cB + (size_t)(t + 2) * kstep;
;             const char* a3 = a2 + kstep; const char* b3 = b2 + kstep;
;             PG8_LDB(B0, 0, 0); PG8_LDB(B1, 0, 1); PG8_SCHED; PG8_LDA(At, 0, 0); PG8_STAGE(PG8_SA(1, 1), a1 + hstepA, voffA);
;     ...
;         if (!(Epi::CHAIN && nxt.b != 0)) {
; #pragma unroll
;         for (int a = 0; a < 2; ++a)
; #pragma unroll
;             for (int b = 0; b < 2; ++b)
; #pragma unroll
;                 for (int m = 0; m < 4; ++m)
; #pragma unroll
;                     for (int n = 0; n < 2; ++n) acc[a][b][m][n] = (f32x4){0.f, 0.f, 0.f, 0.f};
;         }
;         cur = nxt; cA = nA; cB = nB; ++ui;
;         if (wr == 1) PG8_BAR;
.LBB0_509:
	s_ashr_i32 s19, s18, 31
	s_lshl_b64 s[14:15], s[18:19], 19
	s_add_u32 s20, s9, s14
	s_addc_u32 s21, s3, s15
	s_and_b64 s[14:15], s[38:39], exec
	s_cselect_b32 s14, s21, s25
	s_cselect_b32 s15, s20, s24
	s_ashr_i32 s17, s16, 31
	s_lshl_b64 s[22:23], s[16:17], 19
	s_add_u32 s22, s30, s22
	s_addc_u32 s23, s31, s23
	s_and_b64 s[36:37], s[38:39], exec
	s_cselect_b32 s17, s23, s27
	s_cselect_b32 s19, s22, s26
	s_add_u32 s24, s24, 0x40080
	s_addc_u32 s25, s25, 0
	s_add_u32 s49, s26, 0x100
	v_mov_b32_e32 v0, 0
	s_addc_u32 s50, s27, 0
	s_mov_b32 s51, -2
	v_mov_b32_e32 v1, v0
	v_mov_b32_e32 v2, v0
	v_mov_b32_e32 v3, v0
	v_mov_b32_e32 v4, v0
	v_mov_b32_e32 v5, v0
	v_mov_b32_e32 v6, v0
	v_mov_b32_e32 v7, v0
	v_mov_b32_e32 v12, v0
	v_mov_b32_e32 v13, v0
	v_mov_b32_e32 v14, v0
	v_mov_b32_e32 v15, v0
	v_mov_b32_e32 v20, v0
	v_mov_b32_e32 v21, v0
	v_mov_b32_e32 v22, v0
	v_mov_b32_e32 v23, v0
	v_mov_b32_e32 v28, v0
	v_mov_b32_e32 v29, v0
	v_mov_b32_e32 v30, v0
	v_mov_b32_e32 v31, v0
	v_mov_b32_e32 v36, v0
	v_mov_b32_e32 v37, v0
	v_mov_b32_e32 v38, v0
	v_mov_b32_e32 v39, v0
	v_mov_b32_e32 v44, v0
	v_mov_b32_e32 v45, v0
	v_mov_b32_e32 v46, v0
	v_mov_b32_e32 v47, v0
	v_mov_b32_e32 v52, v0
	s_waitcnt lgkmcnt(0)
	v_mov_b32_e32 v53, v0
	v_mov_b32_e32 v54, v0
	v_mov_b32_e32 v55, v0
	v_mov_b32_e32 v8, v0
	v_mov_b32_e32 v9, v0
	v_mov_b32_e32 v10, v0
	v_mov_b32_e32 v11, v0
	v_mov_b32_e32 v16, v0
	v_mov_b32_e32 v17, v0
	v_mov_b32_e32 v18, v0
	v_mov_b32_e32 v19, v0
	v_mov_b32_e32 v24, v0
	v_mov_b32_e32 v25, v0
	v_mov_b32_e32 v26, v0
	v_mov_b32_e32 v27, v0
	v_mov_b32_e32 v32, v0
	v_mov_b32_e32 v33, v0
	v_mov_b32_e32 v34, v0
	v_mov_b32_e32 v35, v0
	v_mov_b32_e32 v40, v0
	v_mov_b32_e32 v41, v0
	v_mov_b32_e32 v42, v0
	v_mov_b32_e32 v43, v0
	v_mov_b32_e32 v48, v0
	v_mov_b32_e32 v49, v0
	v_mov_b32_e32 v50, v0
	v_mov_b32_e32 v51, v0
	v_mov_b32_e32 v56, v0
	v_mov_b32_e32 v57, v0
	v_mov_b32_e32 v58, v0
	v_mov_b32_e32 v59, v0
	v_mov_b32_e32 v60, v0
	v_mov_b32_e32 v61, v0
	v_mov_b32_e32 v62, v0
	v_mov_b32_e32 v63, v0
	v_mov_b32_e32 v64, v0
	v_mov_b32_e32 v65, v0
	v_mov_b32_e32 v66, v0
	v_mov_b32_e32 v67, v0
	v_mov_b32_e32 v68, v0
	v_mov_b32_e32 v69, v0
	v_mov_b32_e32 v70, v0
	v_mov_b32_e32 v71, v0
	v_mov_b32_e32 v76, v0
	v_mov_b32_e32 v77, v0
	v_mov_b32_e32 v78, v0
	v_mov_b32_e32 v79, v0
	v_mov_b32_e32 v84, v0
	v_mov_b32_e32 v85, v0
	v_mov_b32_e32 v86, v0
	v_mov_b32_e32 v87, v0
	v_mov_b32_e32 v92, v0
	v_mov_b32_e32 v93, v0
	v_mov_b32_e32 v94, v0
	v_mov_b32_e32 v95, v0
	v_mov_b32_e32 v100, v0
	v_mov_b32_e32 v101, v0
	v_mov_b32_e32 v102, v0
	v_mov_b32_e32 v103, v0
	v_mov_b32_e32 v108, v0
	v_mov_b32_e32 v109, v0
	v_mov_b32_e32 v110, v0
	v_mov_b32_e32 v111, v0
	v_mov_b32_e32 v116, v0
	v_mov_b32_e32 v117, v0
	v_mov_b32_e32 v118, v0
	v_mov_b32_e32 v119, v0
	v_mov_b32_e32 v72, v0
	v_mov_b32_e32 v73, v0
	v_mov_b32_e32 v74, v0
	v_mov_b32_e32 v75, v0
	v_mov_b32_e32 v80, v0
	v_mov_b32_e32 v81, v0
	v_mov_b32_e32 v82, v0
	v_mov_b32_e32 v83, v0
	v_mov_b32_e32 v88, v0
	v_mov_b32_e32 v89, v0
	v_mov_b32_e32 v90, v0
	v_mov_b32_e32 v91, v0
	v_mov_b32_e32 v96, v0
	v_mov_b32_e32 v97, v0
	v_mov_b32_e32 v98, v0
	v_mov_b32_e32 v99, v0
	v_mov_b32_e32 v104, v0
	v_mov_b32_e32 v105, v0
	v_mov_b32_e32 v106, v0
	v_mov_b32_e32 v107, v0
	v_mov_b32_e32 v112, v0
	v_mov_b32_e32 v113, v0
	v_mov_b32_e32 v114, v0
	v_mov_b32_e32 v115, v0
	v_mov_b32_e32 v120, v0
	v_mov_b32_e32 v121, v0
	v_mov_b32_e32 v122, v0
	v_mov_b32_e32 v123, v0
	v_mov_b32_e32 v124, v0
	v_mov_b32_e32 v125, v0
	v_mov_b32_e32 v126, v0
	v_mov_b32_e32 v127, v0
	s_cmp_eq_u32 s61, 0
	s_cbranch_scc1 .Lp4_nobar
	s_mov_b32 s61, 0
	s_barrier
.Lp4_nobar:
.LBB0_510:
	s_add_u32 s26, s24, 0xfffc0080
	s_addc_u32 s27, s25, -1
	s_add_i32 s52, 0, 0x10000
	s_cmp_eq_u32 s51, 12
	s_cselect_b32 s37, s14, s27
	s_cselect_b32 s36, s15, s26
	s_cselect_b32 s27, s17, s50
	s_cselect_b32 s26, s19, s49
	s_add_i32 s54, 0, 0x14000
	v_add_u32_e32 v140, s52, v178
	v_add_u32_e32 v168, s54, v178
	ds_read_b128 v[128:131], v140
	ds_read_b128 v[132:135], v140 offset:1024
	ds_read_b128 v[136:139], v140 offset:2048
	ds_read_b128 v[140:143], v140 offset:3072
	ds_read_b128 v[144:147], v168
	ds_read_b128 v[148:151], v168 offset:1024
	ds_read_b128 v[152:155], v168 offset:2048
	ds_read_b128 v[168:171], v168 offset:3072
	s_add_i32 m0, s6, 0xc000
	ds_read_b128 v[172:175], v179
	ds_read_b128 v[180:183], v179 offset:1024
	ds_read_b128 v[184:187], v179 offset:2048
	ds_read_b128 v[188:191], v179 offset:3072
	ds_read_b128 v[192:195], v179 offset:4096
	ds_read_b128 v[196:199], v179 offset:5120
	ds_read_b128 v[200:203], v179 offset:6144
	ds_read_b128 v[204:207], v179 offset:7168
	global_load_lds_dwordx4 v164, s[24:25]
	s_add_i32 m0, s6, 0xe000
	s_nop 0
	global_load_lds_dwordx4 v166, s[24:25]
	s_waitcnt vmcnt(8)
	s_waitcnt lgkmcnt(0)
	s_barrier
; #define PG8_STAGE(bufoff, gbase, voff) do { _Pragma("unroll") for (int _i = 0; _i < 2; ++_i) \
;         __builtin_amdgcn_global_load_lds((const unsigned*)((const char*)(gbase) + (voff)[_i]), (LAS unsigned*)(lds + (bufoff) + ldsw + _i * 8192), 16, 0, 0); } while (0)
; #define PG8_LDA(dst, b, h) do { _Pragma("unroll") for (int m = 0; m < 4; ++m) _Pragma("unroll") for (int k = 0; k < 2; ++k) dst[m][k] = *(const LAS bf16x8*)(lds + PG8_SA(b, h) + aoff + m * 2048 + k * 1024); } while (0)
; #define PG8_LDB(dst, b, h) do { _Pragma("unroll") for (int n = 0; n < 2; ++n) _Pragma("unroll") for (int k = 0; k < 2; ++k) dst[n][k] = *(const LAS bf16x8*)(lds + PG8_SB(b, h) + boff + n * 2048 + k * 1024); } while (0)
; #define PG8_MMA(ai, bj, At, Bt) do { __builtin_amdgcn_s_setprio(1); _Pragma("unroll") for (int m = 0; m < 4; ++m) _Pragma("unroll") for (int n = 0; n < 2; ++n) _Pragma("unroll") for (int k = 0; k < 2; ++k) \
;         acc[ai][bj][m][n] = __builtin_amdgcn_mfma_f32_16x16x32_bf16(Bt[n][k], At[m][k], acc[ai][bj][m][n], 0, 0, 0); __builtin_amdgcn_s_setprio(0); } while (0)
; #define PG8_WAIT_V(n) asm volatile("s_waitcnt vmcnt(" #n ")" ::: "memory")
; #define PG8_WAIT_L(n) asm volatile("s_waitcnt lgkmcnt(" #n ")" ::: "memory")
; #define PG8_BAR __builtin_amdgcn_s_barrier()
; #define PG8_SCHED __builtin_amdgcn_sched_barrier(0)
; template <class Epi, class Sched>
; __device__ __forceinline__ void gemm_phase(LAS unsigned char* lds, const Gemm g, const Sched& S, const Epi& E) {
;     ...
;             PG8_LDB(B0, 0, 0); PG8_LDB(B1, 0, 1); PG8_SCHED; PG8_LDA(At, 0, 0); PG8_STAGE(PG8_SA(1, 1), a1 + hstepA, voffA);
;             PG8_WAIT_V(8); PG8_WAIT_L(0); PG8_BAR; PG8_MMA(0, 0, At, B0); PG8_MMA(0, 1, At, B1); PG8_BAR; PG8_SCHED;
;             PG8_LDA(At, 0, 1); PG8_STAGE(PG8_SB(0, 0), b2, voffB); PG8_STAGE(PG8_SB(0, 1), b2 + hstepB, voffB); PG8_STAGE(PG8_SA(0, 0), a2, voffA);
;             PG8_WAIT_V(8); PG8_WAIT_L(0); PG8_BAR; PG8_MMA(1, 0, At, B0); PG8_MMA(1, 1, At, B1); PG8_BAR; PG8_SCHED;
	s_setprio 1
	s_waitcnt lgkmcnt(0)
	v_mfma_f32_16x16x32_bf16 v[124:127], v[128:131], v[172:175], v[124:127]
	v_mfma_f32_16x16x32_bf16 v[120:123], v[136:139], v[172:175], v[120:123]
	v_mfma_f32_16x16x32_bf16 v[112:115], v[128:131], v[184:187], v[112:115]
	v_mfma_f32_16x16x32_bf16 v[104:107], v[136:139], v[184:187], v[104:107]
	v_mfma_f32_16x16x32_bf16 v[96:99], v[128:131], v[192:195], v[96:99]
	v_mfma_f32_16x16x32_bf16 v[88:91], v[136:139], v[192:195], v[88:91]
	v_mfma_f32_16x16x32_bf16 v[80:83], v[128:131], v[200:203], v[80:83]
	v_mfma_f32_16x16x32_bf16 v[72:75], v[136:139], v[200:203], v[72:75]
	v_mfma_f32_16x16x32_bf16 v[124:127], v[132:135], v[180:183], v[124:127]
	v_mfma_f32_16x16x32_bf16 v[120:123], v[140:143], v[180:183], v[120:123]
	v_mfma_f32_16x16x32_bf16 v[112:115], v[132:135], v[188:191], v[112:115]
	v_mfma_f32_16x16x32_bf16 v[104:107], v[140:143], v[188:191], v[104:107]
	v_mfma_f32_16x16x32_bf16 v[96:99], v[132:135], v[196:199], v[96:99]
	v_mfma_f32_16x16x32_bf16 v[88:91], v[140:143], v[196:199], v[88:91]
	v_mfma_f32_16x16x32_bf16 v[80:83], v[132:135], v[204:207], v[80:83]
	v_mfma_f32_16x16x32_bf16 v[72:75], v[140:143], v[204:207], v[72:75]
	s_setprio 0
	s_setprio 1
	v_mfma_f32_16x16x32_bf16 v[116:119], v[144:147], v[172:175], v[116:119]
	v_mfma_f32_16x16x32_bf16 v[108:111], v[152:155], v[172:175], v[108:111]
	v_mfma_f32_16x16x32_bf16 v[100:103], v[144:147], v[184:187], v[100:103]
	v_mfma_f32_16x16x32_bf16 v[92:95], v[152:155], v[184:187], v[92:95]
	v_mfma_f32_16x16x32_bf16 v[84:87], v[144:147], v[192:195], v[84:87]
	v_mfma_f32_16x16x32_bf16 v[76:79], v[152:155], v[192:195], v[76:79]
	v_mfma_f32_16x16x32_bf16 v[68:71], v[144:147], v[200:203], v[68:71]
	v_mfma_f32_16x16x32_bf16 v[64:67], v[152:155], v[200:203], v[64:67]
	v_mfma_f32_16x16x32_bf16 v[116:119], v[148:151], v[180:183], v[116:119]
	v_mfma_f32_16x16x32_bf16 v[108:111], v[168:171], v[180:183], v[108:111]
	v_mfma_f32_16x16x32_bf16 v[100:103], v[148:151], v[188:191], v[100:103]
	v_mfma_f32_16x16x32_bf16 v[92:95], v[168:171], v[188:191], v[92:95]
	v_mfma_f32_16x16x32_bf16 v[84:87], v[148:151], v[196:199], v[84:87]
	v_mfma_f32_16x16x32_bf16 v[76:79], v[168:171], v[196:199], v[76:79]
	v_mfma_f32_16x16x32_bf16 v[68:71], v[148:151], v[204:207], v[68:71]
	v_mfma_f32_16x16x32_bf16 v[64:67], v[168:171], v[204:207], v[64:67]
	s_setprio 0
	s_barrier
	s_add_i32 s52, s52, s2
	s_mov_b32 m0, s52
	ds_read_b128 v[172:175], v179 offset:16384
	ds_read_b128 v[180:183], v179 offset:17408
	ds_read_b128 v[184:187], v179 offset:18432
	ds_read_b128 v[188:191], v179 offset:19456
	ds_read_b128 v[192:195], v179 offset:20480
	ds_read_b128 v[196:199], v179 offset:21504
	ds_read_b128 v[200:203], v179 offset:22528
	ds_read_b128 v[204:207], v179 offset:23552
	global_load_lds_dwordx4 v160, s[26:27]
	s_add_i32 m0, s52, 0x2000
	s_add_u32 s52, s26, 0x40000
	s_addc_u32 s53, s27, 0
	s_add_i32 s54, s54, s2
	global_load_lds_dwordx4 v156, s[26:27]
	s_mov_b32 m0, s54
	s_nop 0
	global_load_lds_dwordx4 v160, s[52:53]
	s_add_i32 m0, s54, 0x2000
	s_nop 0
	global_load_lds_dwordx4 v156, s[52:53]
	s_mov_b32 m0, s6
	s_nop 0
	global_load_lds_dwordx4 v162, s[36:37]
	s_mov_b32 m0, s40
	s_nop 0
	global_load_lds_dwordx4 v158, s[36:37]
	s_waitcnt vmcnt(8)
	s_waitcnt lgkmcnt(0)
	s_barrier
	s_setprio 1
	s_waitcnt lgkmcnt(0)
	v_mfma_f32_16x16x32_bf16 v[60:63], v[128:131], v[172:175], v[60:63]
	v_mfma_f32_16x16x32_bf16 v[56:59], v[136:139], v[172:175], v[56:59]
	v_mfma_f32_16x16x32_bf16 v[48:51], v[128:131], v[184:187], v[48:51]
	v_mfma_f32_16x16x32_bf16 v[40:43], v[136:139], v[184:187], v[40:43]
	v_mfma_f32_16x16x32_bf16 v[32:35], v[128:131], v[192:195], v[32:35]
	v_mfma_f32_16x16x32_bf16 v[24:27], v[136:139], v[192:195], v[24:27]
	v_mfma_f32_16x16x32_bf16 v[16:19], v[128:131], v[200:203], v[16:19]
	v_mfma_f32_16x16x32_bf16 v[8:11], v[136:139], v[200:203], v[8:11]
	v_mfma_f32_16x16x32_bf16 v[60:63], v[132:135], v[180:183], v[60:63]
	v_mfma_f32_16x16x32_bf16 v[56:59], v[140:143], v[180:183], v[56:59]
	v_mfma_f32_16x16x32_bf16 v[48:51], v[132:135], v[188:191], v[48:51]
	v_mfma_f32_16x16x32_bf16 v[40:43], v[140:143], v[188:191], v[40:43]
	v_mfma_f32_16x16x32_bf16 v[32:35], v[132:135], v[196:199], v[32:35]
	v_mfma_f32_16x16x32_bf16 v[24:27], v[140:143], v[196:199], v[24:27]
	v_mfma_f32_16x16x32_bf16 v[16:19], v[132:135], v[204:207], v[16:19]
	v_mfma_f32_16x16x32_bf16 v[8:11], v[140:143], v[204:207], v[8:11]
	s_setprio 0
	s_setprio 1
	v_mfma_f32_16x16x32_bf16 v[52:55], v[144:147], v[172:175], v[52:55]
	v_mfma_f32_16x16x32_bf16 v[44:47], v[152:155], v[172:175], v[44:47]
	v_mfma_f32_16x16x32_bf16 v[36:39], v[144:147], v[184:187], v[36:39]
	v_mfma_f32_16x16x32_bf16 v[28:31], v[152:155], v[184:187], v[28:31]
	v_mfma_f32_16x16x32_bf16 v[20:23], v[144:147], v[192:195], v[20:23]
	v_mfma_f32_16x16x32_bf16 v[12:15], v[152:155], v[192:195], v[12:15]
	v_mfma_f32_16x16x32_bf16 v[4:7], v[144:147], v[200:203], v[4:7]
	v_mfma_f32_16x16x32_bf16 v[0:3], v[152:155], v[200:203], v[0:3]
	v_mfma_f32_16x16x32_bf16 v[52:55], v[148:151], v[180:183], v[52:55]
	v_mfma_f32_16x16x32_bf16 v[44:47], v[168:171], v[180:183], v[44:47]
	v_mfma_f32_16x16x32_bf16 v[36:39], v[148:151], v[188:191], v[36:39]
	v_mfma_f32_16x16x32_bf16 v[28:31], v[168:171], v[188:191], v[28:31]
	v_mfma_f32_16x16x32_bf16 v[20:23], v[148:151], v[196:199], v[20:23]
	v_mfma_f32_16x16x32_bf16 v[12:15], v[168:171], v[196:199], v[12:15]
	v_mfma_f32_16x16x32_bf16 v[4:7], v[148:151], v[204:207], v[4:7]
	v_mfma_f32_16x16x32_bf16 v[0:3], v[168:171], v[204:207], v[0:3]
	s_setprio 0
	s_barrier
; #define PG8_STAGE(bufoff, gbase, voff) do { _Pragma("unroll") for (int _i = 0; _i < 2; ++_i) \
;         __builtin_amdgcn_global_load_lds((const unsigned*)((const char*)(gbase) + (voff)[_i]), (LAS unsigned*)(lds + (bufoff) + ldsw + _i * 8192), 16, 0, 0); } while (0)
; #define PG8_LDA(dst, b, h) do { _Pragma("unroll") for (int m = 0; m < 4; ++m) _Pragma("unroll") for (int k = 0; k < 2; ++k) dst[m][k] = *(const LAS bf16x8*)(lds + PG8_SA(b, h) + aoff + m * 2048 + k * 1024); } while (0)
; #define PG8_LDB(dst, b, h) do { _Pragma("unroll") for (int n = 0; n < 2; ++n) _Pragma("unroll") for (int k = 0; k < 2; ++k) dst[n][k] = *(const LAS bf16x8*)(lds + PG8_SB(b, h) + boff + n * 2048 + k * 1024); } while (0)
; #define PG8_MMA(ai, bj, At, Bt) do { __builtin_amdgcn_s_setprio(1); _Pragma("unroll") for (int m = 0; m < 4; ++m) _Pragma("unroll") for (int n = 0; n < 2; ++n) _Pragma("unroll") for (int k = 0; k < 2; ++k) \
;         acc[ai][bj][m][n] = __builtin_amdgcn_mfma_f32_16x16x32_bf16(Bt[n][k], At[m][k], acc[ai][bj][m][n], 0, 0, 0); __builtin_amdgcn_s_setprio(0); } while (0)
; #define PG8_WAIT_V(n) asm volatile("s_waitcnt vmcnt(" #n ")" ::: "memory")
; #define PG8_WAIT_L(n) asm volatile("s_waitcnt lgkmcnt(" #n ")" ::: "memory")
; #define PG8_BAR __builtin_amdgcn_s_barrier()
; #define PG8_SCHED __builtin_amdgcn_sched_barrier(0)
; template <class Epi, class Sched>
; __device__ __forceinline__ void gemm_phase(LAS unsigned char* lds, const Gemm g, const Sched& S, const Epi& E) {
;     ...
;             PG8_LDB(B0, 1, 0); PG8_LDB(B1, 1, 1); PG8_SCHED; PG8_LDA(At, 1, 0); PG8_STAGE(PG8_SA(0, 1), a2 + hstepA, voffA);
;             PG8_WAIT_V(8); PG8_WAIT_L(0); PG8_BAR; PG8_MMA(0, 0, At, B0); PG8_MMA(0, 1, At, B1); PG8_BAR; PG8_SCHED;
;             PG8_LDA(At, 1, 1); PG8_STAGE(PG8_SB(1, 0), b3, voffB); PG8_STAGE(PG8_SB(1, 1), b3 + hstepB, voffB); PG8_STAGE(PG8_SA(1, 0), a3, voffA);
;             PG8_WAIT_V(8); PG8_WAIT_L(0); PG8_BAR; PG8_MMA(1, 0, At, B0); PG8_MMA(1, 1, At, B1); PG8_BAR; PG8_SCHED;
;         }
;         if (wr == 0) PG8_BAR;
	s_add_i32 s52, 0, 0x18000
	s_add_i32 s53, 0, 0x1c000
	v_add_u32_e32 v140, s52, v178
	v_add_u32_e32 v168, s53, v178
	ds_read_b128 v[128:131], v140
	ds_read_b128 v[132:135], v140 offset:1024
	ds_read_b128 v[136:139], v140 offset:2048
	ds_read_b128 v[140:143], v140 offset:3072
	ds_read_b128 v[144:147], v168
	ds_read_b128 v[148:151], v168 offset:1024
	ds_read_b128 v[152:155], v168 offset:2048
	ds_read_b128 v[168:171], v168 offset:3072
	s_add_u32 s36, s36, 0x40000
	s_addc_u32 s37, s37, 0
	s_mov_b32 m0, s41
	ds_read_b128 v[172:175], v179 offset:32768
	ds_read_b128 v[180:183], v179 offset:33792
	ds_read_b128 v[184:187], v179 offset:34816
	ds_read_b128 v[188:191], v179 offset:35840
	ds_read_b128 v[192:195], v179 offset:36864
	ds_read_b128 v[196:199], v179 offset:37888
	ds_read_b128 v[200:203], v179 offset:38912
	ds_read_b128 v[204:207], v179 offset:39936
	global_load_lds_dwordx4 v162, s[36:37]
	s_mov_b32 m0, s42
	s_nop 0
	global_load_lds_dwordx4 v158, s[36:37]
	s_waitcnt vmcnt(8)
	s_waitcnt lgkmcnt(0)
	s_barrier
	s_setprio 1
	s_waitcnt lgkmcnt(0)
	v_mfma_f32_16x16x32_bf16 v[124:127], v[128:131], v[172:175], v[124:127]
	v_mfma_f32_16x16x32_bf16 v[120:123], v[136:139], v[172:175], v[120:123]
	v_mfma_f32_16x16x32_bf16 v[112:115], v[128:131], v[184:187], v[112:115]
	v_mfma_f32_16x16x32_bf16 v[104:107], v[136:139], v[184:187], v[104:107]
	v_mfma_f32_16x16x32_bf16 v[96:99], v[128:131], v[192:195], v[96:99]
	v_mfma_f32_16x16x32_bf16 v[88:91], v[136:139], v[192:195], v[88:91]
	v_mfma_f32_16x16x32_bf16 v[80:83], v[128:131], v[200:203], v[80:83]
	v_mfma_f32_16x16x32_bf16 v[72:75], v[136:139], v[200:203], v[72:75]
	v_mfma_f32_16x16x32_bf16 v[124:127], v[132:135], v[180:183], v[124:127]
	v_mfma_f32_16x16x32_bf16 v[120:123], v[140:143], v[180:183], v[120:123]
	v_mfma_f32_16x16x32_bf16 v[112:115], v[132:135], v[188:191], v[112:115]
	v_mfma_f32_16x16x32_bf16 v[104:107], v[140:143], v[188:191], v[104:107]
	v_mfma_f32_16x16x32_bf16 v[96:99], v[132:135], v[196:199], v[96:99]
	v_mfma_f32_16x16x32_bf16 v[88:91], v[140:143], v[196:199], v[88:91]
	v_mfma_f32_16x16x32_bf16 v[80:83], v[132:135], v[204:207], v[80:83]
	v_mfma_f32_16x16x32_bf16 v[72:75], v[140:143], v[204:207], v[72:75]
	s_setprio 0
	s_setprio 1
	v_mfma_f32_16x16x32_bf16 v[116:119], v[144:147], v[172:175], v[116:119]
	v_mfma_f32_16x16x32_bf16 v[108:111], v[152:155], v[172:175], v[108:111]
	v_mfma_f32_16x16x32_bf16 v[100:103], v[144:147], v[184:187], v[100:103]
	v_mfma_f32_16x16x32_bf16 v[92:95], v[152:155], v[184:187], v[92:95]
	v_mfma_f32_16x16x32_bf16 v[84:87], v[144:147], v[192:195], v[84:87]
	v_mfma_f32_16x16x32_bf16 v[76:79], v[152:155], v[192:195], v[76:79]
	v_mfma_f32_16x16x32_bf16 v[68:71], v[144:147], v[200:203], v[68:71]
	v_mfma_f32_16x16x32_bf16 v[64:67], v[152:155], v[200:203], v[64:67]
	v_mfma_f32_16x16x32_bf16 v[116:119], v[148:151], v[180:183], v[116:119]
	v_mfma_f32_16x16x32_bf16 v[108:111], v[168:171], v[180:183], v[108:111]
	v_mfma_f32_16x16x32_bf16 v[100:103], v[148:151], v[188:191], v[100:103]
	v_mfma_f32_16x16x32_bf16 v[92:95], v[168:171], v[188:191], v[92:95]
	v_mfma_f32_16x16x32_bf16 v[84:87], v[148:151], v[196:199], v[84:87]
	v_mfma_f32_16x16x32_bf16 v[76:79], v[168:171], v[196:199], v[76:79]
	v_mfma_f32_16x16x32_bf16 v[68:71], v[148:151], v[204:207], v[68:71]
	v_mfma_f32_16x16x32_bf16 v[64:67], v[168:171], v[204:207], v[64:67]
	s_setprio 0
	s_barrier
	s_add_u32 s98, s36, 0xfffc0080
	s_addc_u32 s99, s37, -1
	s_add_u32 s62, s26, 0x80
	s_addc_u32 s63, s27, 0
	s_add_i32 s36, s52, s2
	s_mov_b32 m0, s36
	ds_read_b128 v[172:175], v179 offset:49152
	ds_read_b128 v[180:183], v179 offset:50176
	ds_read_b128 v[184:187], v179 offset:51200
	ds_read_b128 v[188:191], v179 offset:52224
	ds_read_b128 v[192:195], v179 offset:53248
	ds_read_b128 v[196:199], v179 offset:54272
	ds_read_b128 v[200:203], v179 offset:55296
	ds_read_b128 v[204:207], v179 offset:56320
	global_load_lds_dwordx4 v160, s[62:63]
	s_add_i32 m0, s36, 0x2000
	s_add_u32 s26, s26, 0x40080
	s_addc_u32 s27, s27, 0
	s_add_i32 s36, s53, s2
	global_load_lds_dwordx4 v156, s[62:63]
	s_mov_b32 m0, s36
	s_nop 0
	global_load_lds_dwordx4 v160, s[26:27]
	s_add_i32 m0, s36, 0x2000
	s_nop 0
	global_load_lds_dwordx4 v156, s[26:27]
	s_mov_b32 m0, s44
	s_nop 0
	global_load_lds_dwordx4 v162, s[98:99]
	s_mov_b32 m0, s45
	s_nop 0
	global_load_lds_dwordx4 v158, s[98:99]
	s_waitcnt vmcnt(8)
	s_waitcnt lgkmcnt(0)
	s_barrier
	s_setprio 1
	s_waitcnt lgkmcnt(0)
	v_mfma_f32_16x16x32_bf16 v[60:63], v[128:131], v[172:175], v[60:63]
	v_mfma_f32_16x16x32_bf16 v[56:59], v[136:139], v[172:175], v[56:59]
	v_mfma_f32_16x16x32_bf16 v[48:51], v[128:131], v[184:187], v[48:51]
	v_mfma_f32_16x16x32_bf16 v[40:43], v[136:139], v[184:187], v[40:43]
	v_mfma_f32_16x16x32_bf16 v[32:35], v[128:131], v[192:195], v[32:35]
	v_mfma_f32_16x16x32_bf16 v[24:27], v[136:139], v[192:195], v[24:27]
	v_mfma_f32_16x16x32_bf16 v[16:19], v[128:131], v[200:203], v[16:19]
	v_mfma_f32_16x16x32_bf16 v[8:11], v[136:139], v[200:203], v[8:11]
	v_mfma_f32_16x16x32_bf16 v[60:63], v[132:135], v[180:183], v[60:63]
	v_mfma_f32_16x16x32_bf16 v[56:59], v[140:143], v[180:183], v[56:59]
	v_mfma_f32_16x16x32_bf16 v[48:51], v[132:135], v[188:191], v[48:51]
	v_mfma_f32_16x16x32_bf16 v[40:43], v[140:143], v[188:191], v[40:43]
	v_mfma_f32_16x16x32_bf16 v[32:35], v[132:135], v[196:199], v[32:35]
	v_mfma_f32_16x16x32_bf16 v[24:27], v[140:143], v[196:199], v[24:27]
	v_mfma_f32_16x16x32_bf16 v[16:19], v[132:135], v[204:207], v[16:19]
	v_mfma_f32_16x16x32_bf16 v[8:11], v[140:143], v[204:207], v[8:11]
	s_setprio 0
	s_setprio 1
	v_mfma_f32_16x16x32_bf16 v[52:55], v[144:147], v[172:175], v[52:55]
	v_mfma_f32_16x16x32_bf16 v[44:47], v[152:155], v[172:175], v[44:47]
	v_mfma_f32_16x16x32_bf16 v[36:39], v[144:147], v[184:187], v[36:39]
	v_mfma_f32_16x16x32_bf16 v[28:31], v[152:155], v[184:187], v[28:31]
	v_mfma_f32_16x16x32_bf16 v[20:23], v[144:147], v[192:195], v[20:23]
	v_mfma_f32_16x16x32_bf16 v[12:15], v[152:155], v[192:195], v[12:15]
	v_mfma_f32_16x16x32_bf16 v[4:7], v[144:147], v[200:203], v[4:7]
	v_mfma_f32_16x16x32_bf16 v[0:3], v[152:155], v[200:203], v[0:3]
	v_mfma_f32_16x16x32_bf16 v[52:55], v[148:151], v[180:183], v[52:55]
	v_mfma_f32_16x16x32_bf16 v[44:47], v[168:171], v[180:183], v[44:47]
	v_mfma_f32_16x16x32_bf16 v[36:39], v[148:151], v[188:191], v[36:39]
	v_mfma_f32_16x16x32_bf16 v[28:31], v[168:171], v[188:191], v[28:31]
	v_mfma_f32_16x16x32_bf16 v[20:23], v[148:151], v[196:199], v[20:23]
	v_mfma_f32_16x16x32_bf16 v[12:15], v[168:171], v[196:199], v[12:15]
	v_mfma_f32_16x16x32_bf16 v[4:7], v[148:151], v[204:207], v[4:7]
	v_mfma_f32_16x16x32_bf16 v[0:3], v[168:171], v[204:207], v[0:3]
	s_setprio 0
	s_barrier
	s_add_i32 s51, s51, 2
	s_add_u32 s24, s24, 0x100
	s_addc_u32 s25, s25, 0
	s_add_u32 s49, s49, 0x100
	s_addc_u32 s50, s50, 0
	s_cmp_gt_u32 s51, 13
	s_cbranch_scc0 .LBB0_510
	s_and_b64 vcc, exec, s[4:5]
	s_cbranch_vccz .LBB0_513
	s_barrier
; __device__ __forceinline__ unsigned cvt_pk_bf16(float lo, float hi) { unsigned r; asm volatile("v_cvt_pk_bf16_f32 %0, %1, %2" : "=v"(r) : "v"(lo), "v"(hi)); return r; }
;     __device__ __forceinline__ void operator()(f32x4 (&acc)[2][2][4][2], const Unit& u, int wr, int wc, int fr, int fq) const {
;         bf16_t* xb = XR + (size_t)(u.pm * BM + wr * 64) * DM + u.pn * BM;
;         const unsigned lo = (unsigned)(fr * DM + wc * 32 + 8 * fq);
;         u32x4 xv[2][4][2];
; #pragma unroll
;         for (int ai = 0; ai < 2; ++ai)
; #pragma unroll
;             for (int m = 0; m < 4; ++m)
; #pragma unroll
;                 for (int bj = 0; bj < 2; ++bj) xv[ai][m][bj] = *(const u32x4*)(xb + (ai * HALF + m * 16) * DM + bj * HALF + lo);
; #pragma unroll
;         for (int ai = 0; ai < 2; ++ai)
; #pragma unroll
;             for (int m = 0; m < 4; ++m)
; #pragma unroll
;                 for (int bj = 0; bj < 2; ++bj) {
;                     const u32x4 x = xv[ai][m][bj]; const f32x4 v0 = acc[ai][bj][m][0], v1 = acc[ai][bj][m][1];
;                     u32x4 w;
;                     w.x = cvt_pk_bf16(bf_lo(x.x) + v0[0], bf_hi(x.x) + v0[1]); w.y = cvt_pk_bf16(bf_lo(x.y) + v0[2], bf_hi(x.y) + v0[3]);
;                     w.z = cvt_pk_bf16(bf_lo(x.z) + v1[0], bf_hi(x.z) + v1[1]); w.w = cvt_pk_bf16(bf_lo(x.w) + v1[2], bf_hi(x.w) + v1[3]);
;                     *(u32x4*)(xb + (ai * HALF + m * 16) * DM + bj * HALF + lo) = w;
.LBB0_513:
	s_lshl_b32 s14, s48, 8
	s_add_i32 s14, s14, s43
	s_ashr_i32 s15, s14, 31
	s_lshl_b64 s[14:15], s[14:15], 11
	s_add_u32 s17, s34, s14
	s_addc_u32 s19, s35, s15
	s_lshl_b32 s14, s47, 8
	s_ashr_i32 s15, s14, 31
	s_lshl_b64 s[14:15], s[14:15], 1
	s_add_u32 s24, s17, s14
	s_addc_u32 s25, s19, s15
	global_load_dwordx4 v[180:183], v212, s[24:25]
	global_load_dwordx4 v[184:187], v212, s[24:25] offset:256
	v_lshl_add_u64 v[128:129], s[24:25], 0, v[212:213]
	v_add_co_u32_e32 v218, vcc, s11, v128
	s_mov_b32 s14, 0x48000
	s_nop 0
	v_addc_co_u32_e32 v219, vcc, 0, v129, vcc
	global_load_dwordx4 v[188:191], v[218:219], off
	global_load_dwordx4 v[192:195], v[218:219], off offset:256
	v_add_co_u32_e32 v220, vcc, s33, v128
	s_nop 1
	v_addc_co_u32_e32 v221, vcc, 0, v129, vcc
	v_add_co_u32_e32 v176, vcc, s10, v128
	s_nop 1
	v_addc_co_u32_e32 v177, vcc, 0, v129, vcc
	v_add_co_u32_e32 v174, vcc, s69, v128
	s_nop 1
	v_addc_co_u32_e32 v175, vcc, 0, v129, vcc
	v_add_co_u32_e32 v172, vcc, s14, v128
	s_mov_b32 s14, 0x50000
	s_nop 0
	v_addc_co_u32_e32 v173, vcc, 0, v129, vcc
	v_add_co_u32_e32 v170, vcc, s14, v128
	s_mov_b32 s14, 0x58000
	s_nop 0
	v_addc_co_u32_e32 v171, vcc, 0, v129, vcc
	v_add_co_u32_e32 v168, vcc, s14, v128
	s_nop 1
	v_addc_co_u32_e32 v169, vcc, 0, v129, vcc
	global_load_dwordx4 v[196:199], v[220:221], off
	global_load_dwordx4 v[200:203], v[220:221], off offset:256
	global_load_dwordx4 v[204:207], v[176:177], off
	global_load_dwordx4 v[208:211], v[176:177], off offset:256
	global_load_dwordx4 v[214:217], v[174:175], off
	global_load_dwordx4 v[152:155], v[174:175], off offset:256
	global_load_dwordx4 v[148:151], v[172:173], off
	global_load_dwordx4 v[144:147], v[172:173], off offset:256
	global_load_dwordx4 v[140:143], v[170:171], off
	global_load_dwordx4 v[136:139], v[170:171], off offset:256
	global_load_dwordx4 v[132:135], v[168:169], off
	global_load_dwordx4 v[128:131], v[168:169], off offset:256
	s_waitcnt vmcnt(12)
	v_lshlrev_b32_e32 v222, 16, v180
	v_and_b32_e32 v180, 0xffff0000, v180
	v_lshlrev_b32_e32 v226, 16, v184
	v_lshlrev_b32_e32 v223, 16, v181
	v_and_b32_e32 v181, 0xffff0000, v181
	v_lshlrev_b32_e32 v224, 16, v182
	v_and_b32_e32 v182, 0xffff0000, v182
	v_lshlrev_b32_e32 v225, 16, v183
	v_and_b32_e32 v183, 0xffff0000, v183
	v_and_b32_e32 v184, 0xffff0000, v184
	v_lshlrev_b32_e32 v227, 16, v185
	v_and_b32_e32 v185, 0xffff0000, v185
	v_add_f32_e32 v124, v124, v222
	v_add_f32_e32 v125, v125, v180
	v_add_f32_e32 v180, v116, v226
	v_cvt_pk_bf16_f32 v116, v124, v125
	v_lshlrev_b32_e32 v228, 16, v186
	v_and_b32_e32 v186, 0xffff0000, v186
	v_add_f32_e32 v126, v126, v223
	v_add_f32_e32 v127, v127, v181
	v_add_f32_e32 v120, v120, v224
	v_add_f32_e32 v121, v121, v182
	v_add_f32_e32 v122, v122, v225
	v_add_f32_e32 v123, v123, v183
	v_add_f32_e32 v181, v117, v184
	v_add_f32_e32 v182, v118, v227
	v_add_f32_e32 v183, v119, v185
	v_cvt_pk_bf16_f32 v117, v126, v127
	v_cvt_pk_bf16_f32 v118, v120, v121
	v_cvt_pk_bf16_f32 v119, v122, v123
	global_store_dwordx4 v212, v[116:119], s[24:25]
	v_lshlrev_b32_e32 v229, 16, v187
	v_add_f32_e32 v184, v108, v228
	v_and_b32_e32 v116, 0xffff0000, v187
	v_add_f32_e32 v185, v109, v186
	v_cvt_pk_bf16_f32 v108, v180, v181
	v_cvt_pk_bf16_f32 v109, v182, v183
	v_add_f32_e32 v111, v111, v116
	v_add_f32_e32 v186, v110, v229
	v_cvt_pk_bf16_f32 v110, v184, v185
	v_cvt_pk_bf16_f32 v111, v186, v111
	global_store_dwordx4 v212, v[108:111], s[24:25] offset:256
	s_andn2_b64 vcc, exec, s[38:39]
	s_mov_b64 s[14:15], -1
	v_lshlrev_b32_e32 v108, 16, v188
	v_and_b32_e32 v109, 0xffff0000, v188
	v_add_f32_e32 v108, v112, v108
	v_add_f32_e32 v109, v113, v109
	v_cvt_pk_bf16_f32 v108, v108, v109
	v_lshlrev_b32_e32 v109, 16, v189
	v_and_b32_e32 v110, 0xffff0000, v189
	v_add_f32_e32 v109, v114, v109
	v_add_f32_e32 v110, v115, v110
	v_cvt_pk_bf16_f32 v109, v109, v110
	v_lshlrev_b32_e32 v110, 16, v190
	v_add_f32_e32 v104, v104, v110
	v_and_b32_e32 v110, 0xffff0000, v190
	v_add_f32_e32 v105, v105, v110
	v_cvt_pk_bf16_f32 v110, v104, v105
	v_lshlrev_b32_e32 v104, 16, v191
	v_add_f32_e32 v104, v106, v104
	v_and_b32_e32 v105, 0xffff0000, v191
	v_add_f32_e32 v105, v107, v105
	v_cvt_pk_bf16_f32 v111, v104, v105
	v_lshlrev_b32_e32 v104, 16, v192
	v_add_f32_e32 v100, v100, v104
	v_and_b32_e32 v104, 0xffff0000, v192
	v_add_f32_e32 v101, v101, v104
	global_store_dwordx4 v[218:219], v[108:111], off
	v_cvt_pk_bf16_f32 v100, v100, v101
	v_lshlrev_b32_e32 v101, 16, v193
	v_add_f32_e32 v101, v102, v101
	v_and_b32_e32 v102, 0xffff0000, v193
	v_add_f32_e32 v102, v103, v102
	v_cvt_pk_bf16_f32 v101, v101, v102
	v_lshlrev_b32_e32 v102, 16, v194
	v_add_f32_e32 v92, v92, v102
	v_and_b32_e32 v102, 0xffff0000, v194
	v_add_f32_e32 v93, v93, v102
	v_cvt_pk_bf16_f32 v102, v92, v93
	v_lshlrev_b32_e32 v92, 16, v195
	v_and_b32_e32 v93, 0xffff0000, v195
	v_add_f32_e32 v92, v94, v92
	v_add_f32_e32 v93, v95, v93
	v_cvt_pk_bf16_f32 v103, v92, v93
	s_waitcnt vmcnt(14)
	v_lshlrev_b32_e32 v92, 16, v196
	v_and_b32_e32 v93, 0xffff0000, v196
	v_add_f32_e32 v92, v96, v92
	v_add_f32_e32 v93, v97, v93
	global_store_dwordx4 v[218:219], v[100:103], off offset:256
	v_cvt_pk_bf16_f32 v92, v92, v93
	v_lshlrev_b32_e32 v93, 16, v197
	v_and_b32_e32 v94, 0xffff0000, v197
	v_add_f32_e32 v93, v98, v93
	v_add_f32_e32 v94, v99, v94
	v_cvt_pk_bf16_f32 v93, v93, v94
	v_lshlrev_b32_e32 v94, 16, v198
	v_add_f32_e32 v88, v88, v94
	v_and_b32_e32 v94, 0xffff0000, v198
	v_add_f32_e32 v89, v89, v94
	v_cvt_pk_bf16_f32 v94, v88, v89
	v_lshlrev_b32_e32 v88, 16, v199
	v_add_f32_e32 v88, v90, v88
	v_and_b32_e32 v89, 0xffff0000, v199
	v_add_f32_e32 v89, v91, v89
	v_cvt_pk_bf16_f32 v95, v88, v89
	s_waitcnt vmcnt(14)
; __device__ __forceinline__ unsigned cvt_pk_bf16(float lo, float hi) { unsigned r; asm volatile("v_cvt_pk_bf16_f32 %0, %1, %2" : "=v"(r) : "v"(lo), "v"(hi)); return r; }
;     __device__ __forceinline__ void operator()(f32x4 (&acc)[2][2][4][2], const Unit& u, int wr, int wc, int fr, int fq) const {
;     ...
;         for (int ai = 0; ai < 2; ++ai)
; #pragma unroll
;             for (int m = 0; m < 4; ++m)
; #pragma unroll
;                 for (int bj = 0; bj < 2; ++bj) {
;                     const u32x4 x = xv[ai][m][bj]; const f32x4 v0 = acc[ai][bj][m][0], v1 = acc[ai][bj][m][1];
;                     u32x4 w;
;                     w.x = cvt_pk_bf16(bf_lo(x.x) + v0[0], bf_hi(x.x) + v0[1]); w.y = cvt_pk_bf16(bf_lo(x.y) + v0[2], bf_hi(x.y) + v0[3]);
;                     w.z = cvt_pk_bf16(bf_lo(x.z) + v1[0], bf_hi(x.z) + v1[1]); w.w = cvt_pk_bf16(bf_lo(x.w) + v1[2], bf_hi(x.w) + v1[3]);
;                     *(u32x4*)(xb + (ai * HALF + m * 16) * DM + bj * HALF + lo) = w;
	v_lshlrev_b32_e32 v88, 16, v200
	v_add_f32_e32 v84, v84, v88
	v_and_b32_e32 v88, 0xffff0000, v200
	v_add_f32_e32 v85, v85, v88
	global_store_dwordx4 v[220:221], v[92:95], off
	v_cvt_pk_bf16_f32 v84, v84, v85
	v_lshlrev_b32_e32 v85, 16, v201
	v_add_f32_e32 v85, v86, v85
	v_and_b32_e32 v86, 0xffff0000, v201
	v_add_f32_e32 v86, v87, v86
	v_cvt_pk_bf16_f32 v85, v85, v86
	v_lshlrev_b32_e32 v86, 16, v202
	v_add_f32_e32 v76, v76, v86
	v_and_b32_e32 v86, 0xffff0000, v202
	v_add_f32_e32 v77, v77, v86
	v_cvt_pk_bf16_f32 v86, v76, v77
	v_lshlrev_b32_e32 v76, 16, v203
	v_and_b32_e32 v77, 0xffff0000, v203
	v_add_f32_e32 v76, v78, v76
	v_add_f32_e32 v77, v79, v77
	v_cvt_pk_bf16_f32 v87, v76, v77
	s_waitcnt vmcnt(14)
	v_lshlrev_b32_e32 v76, 16, v204
	v_and_b32_e32 v77, 0xffff0000, v204
	v_add_f32_e32 v76, v80, v76
	v_add_f32_e32 v77, v81, v77
	global_store_dwordx4 v[220:221], v[84:87], off offset:256
	v_cvt_pk_bf16_f32 v76, v76, v77
	v_lshlrev_b32_e32 v77, 16, v205
	v_and_b32_e32 v78, 0xffff0000, v205
	v_add_f32_e32 v77, v82, v77
	v_add_f32_e32 v78, v83, v78
	v_cvt_pk_bf16_f32 v77, v77, v78
	v_lshlrev_b32_e32 v78, 16, v206
	v_add_f32_e32 v72, v72, v78
	v_and_b32_e32 v78, 0xffff0000, v206
	v_add_f32_e32 v73, v73, v78
	v_cvt_pk_bf16_f32 v78, v72, v73
	v_lshlrev_b32_e32 v72, 16, v207
	v_add_f32_e32 v72, v74, v72
	v_and_b32_e32 v73, 0xffff0000, v207
	v_add_f32_e32 v73, v75, v73
	v_cvt_pk_bf16_f32 v79, v72, v73
	s_waitcnt vmcnt(14)
	v_lshlrev_b32_e32 v72, 16, v208
	v_add_f32_e32 v68, v68, v72
	v_and_b32_e32 v72, 0xffff0000, v208
	v_add_f32_e32 v69, v69, v72
	global_store_dwordx4 v[176:177], v[76:79], off
	v_cvt_pk_bf16_f32 v68, v68, v69
	v_lshlrev_b32_e32 v69, 16, v209
	v_add_f32_e32 v69, v70, v69
	v_and_b32_e32 v70, 0xffff0000, v209
	v_add_f32_e32 v70, v71, v70
	v_cvt_pk_bf16_f32 v69, v69, v70
	v_lshlrev_b32_e32 v70, 16, v210
	v_add_f32_e32 v64, v64, v70
	v_and_b32_e32 v70, 0xffff0000, v210
	v_add_f32_e32 v65, v65, v70
	v_cvt_pk_bf16_f32 v70, v64, v65
	v_lshlrev_b32_e32 v64, 16, v211
	v_add_f32_e32 v64, v66, v64
	v_and_b32_e32 v65, 0xffff0000, v211
	v_add_f32_e32 v65, v67, v65
	v_cvt_pk_bf16_f32 v71, v64, v65
	s_waitcnt vmcnt(14)
	v_lshlrev_b32_e32 v64, 16, v214
	v_add_f32_e32 v60, v60, v64
	v_and_b32_e32 v64, 0xffff0000, v214
	v_add_f32_e32 v61, v61, v64
	global_store_dwordx4 v[176:177], v[68:71], off offset:256
	v_cvt_pk_bf16_f32 v60, v60, v61
	v_lshlrev_b32_e32 v61, 16, v215
	v_add_f32_e32 v61, v62, v61
	v_and_b32_e32 v62, 0xffff0000, v215
	v_add_f32_e32 v62, v63, v62
	v_cvt_pk_bf16_f32 v61, v61, v62
	v_lshlrev_b32_e32 v62, 16, v216
	v_add_f32_e32 v56, v56, v62
	v_and_b32_e32 v62, 0xffff0000, v216
	v_add_f32_e32 v57, v57, v62
	v_cvt_pk_bf16_f32 v62, v56, v57
	v_lshlrev_b32_e32 v56, 16, v217
	v_add_f32_e32 v56, v58, v56
	v_and_b32_e32 v57, 0xffff0000, v217
	v_add_f32_e32 v57, v59, v57
	v_cvt_pk_bf16_f32 v63, v56, v57
	s_waitcnt vmcnt(14)
	v_lshlrev_b32_e32 v56, 16, v152
	v_add_f32_e32 v52, v52, v56
	v_and_b32_e32 v56, 0xffff0000, v152
	v_add_f32_e32 v53, v53, v56
	global_store_dwordx4 v[174:175], v[60:63], off
	v_cvt_pk_bf16_f32 v52, v52, v53
	v_lshlrev_b32_e32 v53, 16, v153
	v_add_f32_e32 v53, v54, v53
	v_and_b32_e32 v54, 0xffff0000, v153
	v_add_f32_e32 v54, v55, v54
	v_cvt_pk_bf16_f32 v53, v53, v54
	v_lshlrev_b32_e32 v54, 16, v154
	v_add_f32_e32 v44, v44, v54
	v_and_b32_e32 v54, 0xffff0000, v154
	v_add_f32_e32 v45, v45, v54
	v_cvt_pk_bf16_f32 v54, v44, v45
	v_lshlrev_b32_e32 v44, 16, v155
	v_and_b32_e32 v45, 0xffff0000, v155
	v_add_f32_e32 v44, v46, v44
	v_add_f32_e32 v45, v47, v45
	v_cvt_pk_bf16_f32 v55, v44, v45
	s_waitcnt vmcnt(14)
	v_lshlrev_b32_e32 v44, 16, v148
	v_and_b32_e32 v45, 0xffff0000, v148
	v_add_f32_e32 v44, v48, v44
	v_add_f32_e32 v45, v49, v45
	global_store_dwordx4 v[174:175], v[52:55], off offset:256
	v_cvt_pk_bf16_f32 v44, v44, v45
	v_lshlrev_b32_e32 v45, 16, v149
	v_and_b32_e32 v46, 0xffff0000, v149
	v_add_f32_e32 v45, v50, v45
	v_add_f32_e32 v46, v51, v46
	v_cvt_pk_bf16_f32 v45, v45, v46
	v_lshlrev_b32_e32 v46, 16, v150
	v_add_f32_e32 v40, v40, v46
	v_and_b32_e32 v46, 0xffff0000, v150
	v_add_f32_e32 v41, v41, v46
	v_cvt_pk_bf16_f32 v46, v40, v41
	v_lshlrev_b32_e32 v40, 16, v151
	v_add_f32_e32 v40, v42, v40
	v_and_b32_e32 v41, 0xffff0000, v151
	v_add_f32_e32 v41, v43, v41
	v_cvt_pk_bf16_f32 v47, v40, v41
	s_waitcnt vmcnt(14)
; __device__ __forceinline__ unsigned cvt_pk_bf16(float lo, float hi) { unsigned r; asm volatile("v_cvt_pk_bf16_f32 %0, %1, %2" : "=v"(r) : "v"(lo), "v"(hi)); return r; }
; #define PG8_BAR __builtin_amdgcn_s_barrier()
;     __device__ __forceinline__ void operator()(f32x4 (&acc)[2][2][4][2], const Unit& u, int wr, int wc, int fr, int fq) const {
;     ...
;         for (int ai = 0; ai < 2; ++ai)
; #pragma unroll
;             for (int m = 0; m < 4; ++m)
; #pragma unroll
;                 for (int bj = 0; bj < 2; ++bj) {
;                     const u32x4 x = xv[ai][m][bj]; const f32x4 v0 = acc[ai][bj][m][0], v1 = acc[ai][bj][m][1];
;                     u32x4 w;
;                     w.x = cvt_pk_bf16(bf_lo(x.x) + v0[0], bf_hi(x.x) + v0[1]); w.y = cvt_pk_bf16(bf_lo(x.y) + v0[2], bf_hi(x.y) + v0[3]);
;                     w.z = cvt_pk_bf16(bf_lo(x.z) + v1[0], bf_hi(x.z) + v1[1]); w.w = cvt_pk_bf16(bf_lo(x.w) + v1[2], bf_hi(x.w) + v1[3]);
;                     *(u32x4*)(xb + (ai * HALF + m * 16) * DM + bj * HALF + lo) = w;
; template <class Epi, class Sched>
; __device__ __forceinline__ void gemm_phase(LAS unsigned char* lds, const Gemm g, const Sched& S, const Epi& E) {
;     ...
;         if (!has_next) break;
;         if (!(Epi::CHAIN && nxt.b != 0)) {
; #pragma unroll
;         for (int a = 0; a < 2; ++a)
; #pragma unroll
;             for (int b = 0; b < 2; ++b)
; #pragma unroll
;                 for (int m = 0; m < 4; ++m)
; #pragma unroll
;                     for (int n = 0; n < 2; ++n) acc[a][b][m][n] = (f32x4){0.f, 0.f, 0.f, 0.f};
;         }
;         cur = nxt; cA = nA; cB = nB; ++ui;
;         if (wr == 1) PG8_BAR;
	v_lshlrev_b32_e32 v40, 16, v144
	v_add_f32_e32 v36, v36, v40
	v_and_b32_e32 v40, 0xffff0000, v144
	v_add_f32_e32 v37, v37, v40
	global_store_dwordx4 v[172:173], v[44:47], off
	v_cvt_pk_bf16_f32 v36, v36, v37
	v_lshlrev_b32_e32 v37, 16, v145
	v_add_f32_e32 v37, v38, v37
	v_and_b32_e32 v38, 0xffff0000, v145
	v_add_f32_e32 v38, v39, v38
	v_cvt_pk_bf16_f32 v37, v37, v38
	v_lshlrev_b32_e32 v38, 16, v146
	v_add_f32_e32 v28, v28, v38
	v_and_b32_e32 v38, 0xffff0000, v146
	v_add_f32_e32 v29, v29, v38
	v_cvt_pk_bf16_f32 v38, v28, v29
	v_lshlrev_b32_e32 v28, 16, v147
	v_and_b32_e32 v29, 0xffff0000, v147
	v_add_f32_e32 v28, v30, v28
	v_add_f32_e32 v29, v31, v29
	v_cvt_pk_bf16_f32 v39, v28, v29
	s_waitcnt vmcnt(14)
	v_lshlrev_b32_e32 v28, 16, v140
	v_and_b32_e32 v29, 0xffff0000, v140
	v_add_f32_e32 v28, v32, v28
	v_add_f32_e32 v29, v33, v29
	global_store_dwordx4 v[172:173], v[36:39], off offset:256
	v_cvt_pk_bf16_f32 v28, v28, v29
	v_lshlrev_b32_e32 v29, 16, v141
	v_and_b32_e32 v30, 0xffff0000, v141
	v_add_f32_e32 v29, v34, v29
	v_add_f32_e32 v30, v35, v30
	v_cvt_pk_bf16_f32 v29, v29, v30
	v_lshlrev_b32_e32 v30, 16, v142
	v_add_f32_e32 v24, v24, v30
	v_and_b32_e32 v30, 0xffff0000, v142
	v_add_f32_e32 v25, v25, v30
	v_cvt_pk_bf16_f32 v30, v24, v25
	v_lshlrev_b32_e32 v24, 16, v143
	v_add_f32_e32 v24, v26, v24
	v_and_b32_e32 v25, 0xffff0000, v143
	v_add_f32_e32 v25, v27, v25
	v_cvt_pk_bf16_f32 v31, v24, v25
	s_waitcnt vmcnt(14)
	v_lshlrev_b32_e32 v24, 16, v136
	v_add_f32_e32 v20, v20, v24
	v_and_b32_e32 v24, 0xffff0000, v136
	v_add_f32_e32 v21, v21, v24
	global_store_dwordx4 v[170:171], v[28:31], off
	v_cvt_pk_bf16_f32 v20, v20, v21
	v_lshlrev_b32_e32 v21, 16, v137
	v_add_f32_e32 v21, v22, v21
	v_and_b32_e32 v22, 0xffff0000, v137
	v_add_f32_e32 v22, v23, v22
	v_cvt_pk_bf16_f32 v21, v21, v22
	v_lshlrev_b32_e32 v22, 16, v138
	v_add_f32_e32 v12, v12, v22
	v_and_b32_e32 v22, 0xffff0000, v138
	v_add_f32_e32 v13, v13, v22
	v_cvt_pk_bf16_f32 v22, v12, v13
	v_lshlrev_b32_e32 v12, 16, v139
	v_and_b32_e32 v13, 0xffff0000, v139
	v_add_f32_e32 v12, v14, v12
	v_add_f32_e32 v13, v15, v13
	v_cvt_pk_bf16_f32 v23, v12, v13
	s_waitcnt vmcnt(14)
	v_lshlrev_b32_e32 v12, 16, v132
	v_and_b32_e32 v13, 0xffff0000, v132
	v_add_f32_e32 v12, v16, v12
	v_add_f32_e32 v13, v17, v13
	global_store_dwordx4 v[170:171], v[20:23], off offset:256
	v_cvt_pk_bf16_f32 v12, v12, v13
	v_lshlrev_b32_e32 v13, 16, v133
	v_and_b32_e32 v14, 0xffff0000, v133
	v_add_f32_e32 v13, v18, v13
	v_add_f32_e32 v14, v19, v14
	v_cvt_pk_bf16_f32 v13, v13, v14
	v_lshlrev_b32_e32 v14, 16, v134
	v_add_f32_e32 v8, v8, v14
	v_and_b32_e32 v14, 0xffff0000, v134
	v_add_f32_e32 v9, v9, v14
	v_cvt_pk_bf16_f32 v14, v8, v9
	v_lshlrev_b32_e32 v8, 16, v135
	v_add_f32_e32 v8, v10, v8
	v_and_b32_e32 v9, 0xffff0000, v135
	v_add_f32_e32 v9, v11, v9
	v_cvt_pk_bf16_f32 v15, v8, v9
	s_waitcnt vmcnt(14)
	v_lshlrev_b32_e32 v8, 16, v128
	v_add_f32_e32 v4, v4, v8
	v_and_b32_e32 v8, 0xffff0000, v128
	v_add_f32_e32 v5, v5, v8
	global_store_dwordx4 v[168:169], v[12:15], off
	v_cvt_pk_bf16_f32 v4, v4, v5
	v_lshlrev_b32_e32 v5, 16, v129
	v_add_f32_e32 v5, v6, v5
	v_and_b32_e32 v6, 0xffff0000, v129
	v_add_f32_e32 v6, v7, v6
	v_cvt_pk_bf16_f32 v5, v5, v6
	v_lshlrev_b32_e32 v6, 16, v130
	v_add_f32_e32 v0, v0, v6
	v_and_b32_e32 v6, 0xffff0000, v130
	v_add_f32_e32 v1, v1, v6
	v_cvt_pk_bf16_f32 v6, v0, v1
	v_lshlrev_b32_e32 v0, 16, v131
	v_and_b32_e32 v1, 0xffff0000, v131
	v_add_f32_e32 v0, v2, v0
	v_add_f32_e32 v1, v3, v1
	v_cvt_pk_bf16_f32 v7, v0, v1
	global_store_dwordx4 v[168:169], v[4:7], off offset:256
	s_cbranch_vccnz .LBB0_502
	s_andn2_b64 vcc, exec, s[0:1]
	s_cbranch_vccnz .LBB0_501
	s_mov_b32 s61, 1
	s_branch .LBB0_501
